# loop tail: the six stale leading vmcnt waits (they guarded staging registers against the removed duplicate loads) dropped, vmcnt(0) kept
# speedup vs baseline: 1.0063x; 1.0015x over previous
.Ltail_133:
	ds_read_b128 v[98:101], v130
	ds_read_b128 v[102:105], v131 offset:36864
	ds_read_b128 v[106:109], v130 offset:32
	ds_read_b128 v[110:113], v131 offset:36896
	ds_read_b128 v[114:117], v131 offset:41472
	ds_read_b128 v[118:121], v130 offset:4608
	ds_read_b128 v[122:125], v130 offset:4640
	s_waitcnt vmcnt(0)
	ds_read_b128 v[126:129], v131 offset:41504
	s_waitcnt lgkmcnt(3)
	v_mfma_f32_32x32x16_bf16 v[34:49], v[98:101], v[114:117], v[34:49]
	ds_write_b128 v139, v[94:97] offset:18432
	v_mfma_f32_32x32x16_bf16 v[50:65], v[98:101], v[102:105], v[50:65]
	s_waitcnt lgkmcnt(3)
	v_mfma_f32_32x32x16_bf16 v[18:33], v[118:121], v[102:105], v[18:33]
	ds_write_b128 v139, v[90:93] offset:55296
	v_mfma_f32_32x32x16_bf16 v[2:17], v[118:121], v[114:117], v[2:17]
	v_mfma_f32_32x32x16_bf16 v[50:65], v[106:109], v[110:113], v[50:65]
	ds_read_b128 v[90:93], v130 offset:64
	ds_read_b128 v[94:97], v130 offset:4672
	ds_read_b128 v[98:101], v131 offset:36928
	ds_read_b128 v[102:105], v131 offset:41536
	ds_write_b128 v139, v[86:89] offset:23040
	s_waitcnt lgkmcnt(7)
	v_mfma_f32_32x32x16_bf16 v[34:49], v[106:109], v[126:129], v[34:49]
	v_mfma_f32_32x32x16_bf16 v[18:33], v[122:125], v[110:113], v[18:33]
	ds_write_b128 v139, v[82:85] offset:59904
	v_mfma_f32_32x32x16_bf16 v[2:17], v[122:125], v[126:129], v[2:17]
	s_waitcnt lgkmcnt(3)
	v_mfma_f32_32x32x16_bf16 v[50:65], v[90:93], v[98:101], v[50:65]
	ds_read_b128 v[82:85], v130 offset:96
	ds_read_b128 v[86:89], v130 offset:4704
	ds_read_b128 v[106:109], v131 offset:36960
	ds_read_b128 v[110:113], v131 offset:41568
	ds_write_b128 v139, v[78:81] offset:27648
	s_waitcnt lgkmcnt(7)
	v_mfma_f32_32x32x16_bf16 v[34:49], v[90:93], v[102:105], v[34:49]
	v_mfma_f32_32x32x16_bf16 v[18:33], v[94:97], v[98:101], v[18:33]
	ds_write_b128 v139, v[74:77] offset:64512
	v_mfma_f32_32x32x16_bf16 v[2:17], v[94:97], v[102:105], v[2:17]
	s_waitcnt lgkmcnt(3)
	v_mfma_f32_32x32x16_bf16 v[50:65], v[82:85], v[106:109], v[50:65]
	ds_write_b128 v139, v[70:73] offset:32256
	s_waitcnt lgkmcnt(3)
	v_mfma_f32_32x32x16_bf16 v[34:49], v[82:85], v[110:113], v[34:49]
	v_mfma_f32_32x32x16_bf16 v[18:33], v[86:89], v[106:109], v[18:33]
	ds_write_b128 v142, v[66:69] offset:13824
	v_mfma_f32_32x32x16_bf16 v[2:17], v[86:89], v[110:113], v[2:17]
	s_waitcnt lgkmcnt(0)
	s_barrier
	ds_read_b128 v[66:69], v130 offset:18432
	ds_read_b128 v[70:73], v131 offset:55296
	ds_read_b128 v[74:77], v130 offset:18464
	ds_read_b128 v[78:81], v131 offset:55328
	ds_read_b128 v[82:85], v131 offset:59904
	ds_read_b128 v[86:89], v130 offset:23040
	ds_read_b128 v[90:93], v130 offset:23072
	ds_read_b128 v[94:97], v131 offset:59936
	s_waitcnt lgkmcnt(6)
	v_mfma_f32_32x32x16_bf16 v[50:65], v[66:69], v[70:73], v[50:65]
	s_waitcnt lgkmcnt(3)
	v_mfma_f32_32x32x16_bf16 v[34:49], v[66:69], v[82:85], v[34:49]
	s_waitcnt lgkmcnt(2)
	v_mfma_f32_32x32x16_bf16 v[18:33], v[86:89], v[70:73], v[18:33]
	v_mfma_f32_32x32x16_bf16 v[2:17], v[86:89], v[82:85], v[2:17]
	v_mfma_f32_32x32x16_bf16 v[50:65], v[74:77], v[78:81], v[50:65]
	ds_read_b128 v[66:69], v130 offset:18496
	ds_read_b128 v[70:73], v130 offset:23104
	ds_read_b128 v[82:85], v131 offset:55360
	ds_read_b128 v[86:89], v131 offset:59968
	s_waitcnt lgkmcnt(4)
	v_mfma_f32_32x32x16_bf16 v[34:49], v[74:77], v[94:97], v[34:49]
	v_mfma_f32_32x32x16_bf16 v[18:33], v[90:93], v[78:81], v[18:33]
	v_mfma_f32_32x32x16_bf16 v[2:17], v[90:93], v[94:97], v[2:17]
	s_waitcnt lgkmcnt(1)
	v_mfma_f32_32x32x16_bf16 v[50:65], v[66:69], v[82:85], v[50:65]
	ds_read_b128 v[74:77], v130 offset:18528
	ds_read_b128 v[78:81], v130 offset:23136
	ds_read_b128 v[90:93], v131 offset:55392
	ds_read_b128 v[94:97], v131 offset:60000
	s_waitcnt lgkmcnt(4)
	v_mfma_f32_32x32x16_bf16 v[34:49], v[66:69], v[86:89], v[34:49]
	v_mfma_f32_32x32x16_bf16 v[18:33], v[70:73], v[82:85], v[18:33]
	v_mfma_f32_32x32x16_bf16 v[2:17], v[70:73], v[86:89], v[2:17]
	s_waitcnt lgkmcnt(1)
	v_mfma_f32_32x32x16_bf16 v[50:65], v[74:77], v[90:93], v[50:65]
	s_waitcnt lgkmcnt(0)
	v_mfma_f32_32x32x16_bf16 v[34:49], v[74:77], v[94:97], v[34:49]
	v_mfma_f32_32x32x16_bf16 v[18:33], v[78:81], v[90:93], v[18:33]
	v_mfma_f32_32x32x16_bf16 v[2:17], v[78:81], v[94:97], v[2:17]
	v_lshrrev_b32_e32 v227, 5, v136
	s_lshl_b32 s0, s51, 9
	v_lshl_add_u32 v223, v227, 12, v222
	v_add_u32_e32 v223, s0, v223
	v_mov_b32_e32 v228, v223
	global_load_dwordx4 v[98:101], v228, s[68:69]
	v_add_u32_e32 v228, 0x8000, v228
	global_load_dwordx4 v[102:105], v228, s[68:69]
	v_add_u32_e32 v228, 0x8000, v228
	global_load_dwordx4 v[106:109], v228, s[68:69]
	v_add_u32_e32 v228, 0x8000, v228
	global_load_dwordx4 v[110:113], v228, s[68:69]
	v_add_u32_e32 v228, 0x8000, v228
	global_load_dwordx4 v[114:117], v228, s[68:69]
	v_add_u32_e32 v228, 0x8000, v228
	global_load_dwordx4 v[118:121], v228, s[68:69]
	v_add_u32_e32 v228, 0x8000, v228
	global_load_dwordx4 v[122:125], v228, s[68:69]
	v_add_u32_e32 v228, 0x8000, v228
	global_load_dwordx4 v[126:129], v228, s[68:69]
	v_add_u32_e32 v228, 0x8000, v228
	global_load_dwordx4 v[178:181], v228, s[68:69]
	v_add_u32_e32 v228, 0x8000, v228
	global_load_dwordx4 v[182:185], v228, s[68:69]
	v_add_u32_e32 v228, 0x8000, v228
	global_load_dwordx4 v[186:189], v228, s[68:69]
	v_add_u32_e32 v228, 0x8000, v228
	global_load_dwordx4 v[190:193], v228, s[68:69]
	v_add_u32_e32 v228, 0x8000, v228
	global_load_dwordx4 v[194:197], v228, s[68:69]
	v_add_u32_e32 v228, 0x8000, v228
	global_load_dwordx4 v[198:201], v228, s[68:69]
	v_add_u32_e32 v228, 0x8000, v228
	global_load_dwordx4 v[202:205], v228, s[68:69]
	v_add_u32_e32 v228, 0x8000, v228
	global_load_dwordx4 v[206:209], v228, s[68:69]
	v_lshl_or_b32 v66, v138, 2, v141
	s_movk_i32 s0, 0x210
	v_and_or_b32 v67, v136, 64, v137
	v_mul_lo_u32 v66, v66, s0
	v_lshl_add_u32 v66, v67, 2, v66
	s_barrier
	s_nop 3
	ds_write2_b32 v66, v50, v34 offset1:32
	ds_write2_b32 v66, v51, v35 offset0:132 offset1:164
	v_add_u32_e32 v34, 0x400, v66
	ds_write2_b32 v34, v52, v36 offset0:8 offset1:40
	ds_write2_b32 v34, v53, v37 offset0:140 offset1:172
	v_add_u32_e32 v34, 0x1000, v66
	ds_write2_b32 v34, v54, v38 offset0:32 offset1:64
	ds_write2_b32 v34, v55, v39 offset0:164 offset1:196
	v_add_u32_e32 v34, 0x1400, v66
	ds_write2_b32 v34, v56, v40 offset0:40 offset1:72
	ds_write2_b32 v34, v57, v41 offset0:172 offset1:204
	v_add_u32_e32 v34, 0x2000, v66
	ds_write2_b32 v34, v58, v42 offset0:64 offset1:96
	ds_write2_b32 v34, v59, v43 offset0:196 offset1:228
	v_add_u32_e32 v34, 0x2400, v66
	ds_write2_b32 v34, v60, v44 offset0:72 offset1:104
	ds_write2_b32 v34, v61, v45 offset0:204 offset1:236
	v_add_u32_e32 v34, 0x3000, v66
	ds_write2_b32 v34, v62, v46 offset0:96 offset1:128
	v_add_u32_e32 v34, 0x3200, v66
	ds_write2_b32 v34, v63, v47 offset0:100 offset1:132
	v_add_u32_e32 v34, 0x3400, v66
	ds_write2_b32 v34, v64, v48 offset0:104 offset1:136
	v_add_u32_e32 v34, 0x3600, v66
	ds_write2_b32 v34, v65, v49 offset0:108 offset1:140
	v_add_u32_e32 v34, 0x4000, v66
	ds_write2_b32 v34, v18, v2 offset0:128 offset1:160
	v_add_u32_e32 v2, 0x4400, v66
	ds_write2_b32 v2, v19, v3 offset0:4 offset1:36
	ds_write2_b32 v2, v20, v4 offset0:136 offset1:168
	v_add_u32_e32 v2, 0x4800, v66
	ds_write2_b32 v2, v21, v5 offset0:12 offset1:44
	v_add_u32_e32 v2, 0x5000, v66
	ds_write2_b32 v2, v22, v6 offset0:160 offset1:192
	v_add_u32_e32 v2, 0x5400, v66
	ds_write2_b32 v2, v23, v7 offset0:36 offset1:68
	ds_write2_b32 v2, v24, v8 offset0:168 offset1:200
	v_add_u32_e32 v2, 0x5800, v66
	ds_write2_b32 v2, v25, v9 offset0:44 offset1:76
	v_add_u32_e32 v2, 0x6000, v66
	ds_write2_b32 v2, v26, v10 offset0:192 offset1:224
	v_add_u32_e32 v2, 0x6400, v66
	ds_write2_b32 v2, v27, v11 offset0:68 offset1:100
	ds_write2_b32 v2, v28, v12 offset0:200 offset1:232
	v_add_u32_e32 v2, 0x6800, v66
	ds_write2_b32 v2, v29, v13 offset0:76 offset1:108
	v_add_u32_e32 v2, 0x7200, v66
	ds_write2_b32 v2, v30, v14 offset0:96 offset1:128
	v_add_u32_e32 v2, 0x7400, v66
	ds_write2_b32 v2, v31, v15 offset0:100 offset1:132
	v_add_u32_e32 v2, 0x7600, v66
	ds_write2_b32 v2, v32, v16 offset0:104 offset1:136
	v_add_u32_e32 v2, 0x7800, v66
	ds_write2_b32 v2, v33, v17 offset0:108 offset1:140
	s_waitcnt lgkmcnt(0)
	s_barrier
	v_lshrrev_b32_e32 v227, 5, v136
	v_mul_u32_u24_e32 v225, 0x210, v227
	v_add_u32_e32 v225, v225, v222
	ds_read_b128 v[2:5], v225
	ds_read_b128 v[6:9], v225 offset:4224
	ds_read_b128 v[10:13], v225 offset:8448
	ds_read_b128 v[14:17], v225 offset:12672
	ds_read_b128 v[18:21], v225 offset:16896
	ds_read_b128 v[22:25], v225 offset:21120
	ds_read_b128 v[26:29], v225 offset:25344
	ds_read_b128 v[30:33], v225 offset:29568
	ds_read_b128 v[34:37], v225 offset:33792
	ds_read_b128 v[38:41], v225 offset:38016
	ds_read_b128 v[42:45], v225 offset:42240
	ds_read_b128 v[46:49], v225 offset:46464
	ds_read_b128 v[50:53], v225 offset:50688
	ds_read_b128 v[54:57], v225 offset:54912
	ds_read_b128 v[58:61], v225 offset:59136
	ds_read_b128 v[62:65], v225 offset:63360
	v_mul_u32_u24_e32 v224, 0x880, v227
	s_lshl_b32 s0, s51, 8
	v_lshrrev_b32_e32 v228, 1, v222
	v_add3_u32 v224, v224, v228, s0
	v_lshlrev_b32_e32 v226, 2, v227
	s_waitcnt lgkmcnt(0)
	s_waitcnt vmcnt(15)
	v_pk_fma_f32 v[2:3], v[2:3], v[210:211], v[98:99]
	v_pk_fma_f32 v[4:5], v[4:5], v[212:213], v[100:101]
	s_waitcnt vmcnt(14)
	v_pk_fma_f32 v[6:7], v[6:7], v[210:211], v[102:103]
	v_pk_fma_f32 v[8:9], v[8:9], v[212:213], v[104:105]
	s_waitcnt vmcnt(13)
	v_pk_fma_f32 v[10:11], v[10:11], v[210:211], v[106:107]
	v_pk_fma_f32 v[12:13], v[12:13], v[212:213], v[108:109]
	s_waitcnt vmcnt(12)
	v_pk_fma_f32 v[14:15], v[14:15], v[210:211], v[110:111]
	v_pk_fma_f32 v[16:17], v[16:17], v[212:213], v[112:113]
	s_waitcnt vmcnt(11)
	v_pk_fma_f32 v[18:19], v[18:19], v[210:211], v[114:115]
	v_pk_fma_f32 v[20:21], v[20:21], v[212:213], v[116:117]
	s_waitcnt vmcnt(10)
	v_pk_fma_f32 v[22:23], v[22:23], v[210:211], v[118:119]
	v_pk_fma_f32 v[24:25], v[24:25], v[212:213], v[120:121]
	s_waitcnt vmcnt(9)
	v_pk_fma_f32 v[26:27], v[26:27], v[210:211], v[122:123]
	v_pk_fma_f32 v[28:29], v[28:29], v[212:213], v[124:125]
	s_waitcnt vmcnt(8)
	v_pk_fma_f32 v[30:31], v[30:31], v[210:211], v[126:127]
	v_pk_fma_f32 v[32:33], v[32:33], v[212:213], v[128:129]
	s_waitcnt vmcnt(7)
	v_pk_fma_f32 v[34:35], v[34:35], v[210:211], v[178:179]
	v_pk_fma_f32 v[36:37], v[36:37], v[212:213], v[180:181]
	s_waitcnt vmcnt(6)
	v_pk_fma_f32 v[38:39], v[38:39], v[210:211], v[182:183]
	v_pk_fma_f32 v[40:41], v[40:41], v[212:213], v[184:185]
	s_waitcnt vmcnt(5)
	v_pk_fma_f32 v[42:43], v[42:43], v[210:211], v[186:187]
	v_pk_fma_f32 v[44:45], v[44:45], v[212:213], v[188:189]
	s_waitcnt vmcnt(4)
	v_pk_fma_f32 v[46:47], v[46:47], v[210:211], v[190:191]
	v_pk_fma_f32 v[48:49], v[48:49], v[212:213], v[192:193]
	s_waitcnt vmcnt(3)
	v_pk_fma_f32 v[50:51], v[50:51], v[210:211], v[194:195]
	v_pk_fma_f32 v[52:53], v[52:53], v[212:213], v[196:197]
	s_waitcnt vmcnt(2)
	v_pk_fma_f32 v[54:55], v[54:55], v[210:211], v[198:199]
	v_pk_fma_f32 v[56:57], v[56:57], v[212:213], v[200:201]
	s_waitcnt vmcnt(1)
	v_pk_fma_f32 v[58:59], v[58:59], v[210:211], v[202:203]
	v_pk_fma_f32 v[60:61], v[60:61], v[212:213], v[204:205]
	s_waitcnt vmcnt(0)
	v_pk_fma_f32 v[62:63], v[62:63], v[210:211], v[206:207]
	v_pk_fma_f32 v[64:65], v[64:65], v[212:213], v[208:209]
	v_mov_b32_e32 v228, v223
	global_store_dwordx4 v228, v[2:5], s[70:71] sc0 sc1
	v_add_u32_e32 v228, 0x8000, v228
	global_store_dwordx4 v228, v[6:9], s[70:71] sc0 sc1
	v_add_u32_e32 v228, 0x8000, v228
	global_store_dwordx4 v228, v[10:13], s[70:71] sc0 sc1
	v_add_u32_e32 v228, 0x8000, v228
	global_store_dwordx4 v228, v[14:17], s[70:71] sc0 sc1
	v_add_u32_e32 v228, 0x8000, v228
	global_store_dwordx4 v228, v[18:21], s[70:71] sc0 sc1
	v_add_u32_e32 v228, 0x8000, v228
	global_store_dwordx4 v228, v[22:25], s[70:71] sc0 sc1
	v_add_u32_e32 v228, 0x8000, v228
	global_store_dwordx4 v228, v[26:29], s[70:71] sc0 sc1
	v_add_u32_e32 v228, 0x8000, v228
	global_store_dwordx4 v228, v[30:33], s[70:71] sc0 sc1
	v_add_u32_e32 v228, 0x8000, v228
	global_store_dwordx4 v228, v[34:37], s[70:71] sc0 sc1
	v_add_u32_e32 v228, 0x8000, v228
	global_store_dwordx4 v228, v[38:41], s[70:71] sc0 sc1
	v_add_u32_e32 v228, 0x8000, v228
	global_store_dwordx4 v228, v[42:45], s[70:71] sc0 sc1
	v_add_u32_e32 v228, 0x8000, v228
	global_store_dwordx4 v228, v[46:49], s[70:71] sc0 sc1
	v_add_u32_e32 v228, 0x8000, v228
	global_store_dwordx4 v228, v[50:53], s[70:71] sc0 sc1
	v_add_u32_e32 v228, 0x8000, v228
	global_store_dwordx4 v228, v[54:57], s[70:71] sc0 sc1
	v_add_u32_e32 v228, 0x8000, v228
	global_store_dwordx4 v228, v[58:61], s[70:71] sc0 sc1
	v_add_u32_e32 v228, 0x8000, v228
	global_store_dwordx4 v228, v[62:65], s[70:71] sc0 sc1
	s_cmp_lg_u64 s[54:55], 0
	s_cbranch_scc0 .LBB0_122
	v_pk_add_f32 v[218:219], v[218:219], 1.0 op_sel_hi:[1,0]
	v_pk_add_f32 v[220:221], v[220:221], 1.0 op_sel_hi:[1,0]
	v_pk_mul_f32 v[214:215], v[214:215], v[218:219]
	v_pk_mul_f32 v[216:217], v[216:217], v[220:221]
	v_pk_mul_f32 v[98:99], v[2:3], v[2:3]
	v_pk_mul_f32 v[100:101], v[4:5], v[4:5]
	v_pk_mul_f32 v[102:103], v[6:7], v[6:7]
	v_pk_mul_f32 v[104:105], v[8:9], v[8:9]
	v_pk_mul_f32 v[106:107], v[10:11], v[10:11]
	v_pk_mul_f32 v[108:109], v[12:13], v[12:13]
	v_pk_mul_f32 v[110:111], v[14:15], v[14:15]
	v_pk_mul_f32 v[112:113], v[16:17], v[16:17]
	v_pk_mul_f32 v[114:115], v[18:19], v[18:19]
	v_pk_mul_f32 v[116:117], v[20:21], v[20:21]
	v_pk_mul_f32 v[118:119], v[22:23], v[22:23]
	v_pk_mul_f32 v[120:121], v[24:25], v[24:25]
	v_pk_mul_f32 v[122:123], v[26:27], v[26:27]
	v_pk_mul_f32 v[124:125], v[28:29], v[28:29]
	v_pk_mul_f32 v[126:127], v[30:31], v[30:31]
	v_pk_mul_f32 v[128:129], v[32:33], v[32:33]
	v_pk_mul_f32 v[178:179], v[34:35], v[34:35]
	v_pk_mul_f32 v[180:181], v[36:37], v[36:37]
	v_pk_mul_f32 v[182:183], v[38:39], v[38:39]
	v_pk_mul_f32 v[184:185], v[40:41], v[40:41]
	v_pk_mul_f32 v[186:187], v[42:43], v[42:43]
	v_pk_mul_f32 v[188:189], v[44:45], v[44:45]
	v_pk_mul_f32 v[190:191], v[46:47], v[46:47]
	v_pk_mul_f32 v[192:193], v[48:49], v[48:49]
	v_pk_mul_f32 v[194:195], v[50:51], v[50:51]
	v_pk_mul_f32 v[196:197], v[52:53], v[52:53]
	v_pk_mul_f32 v[198:199], v[54:55], v[54:55]
	v_pk_mul_f32 v[200:201], v[56:57], v[56:57]
	v_pk_mul_f32 v[202:203], v[58:59], v[58:59]
	v_pk_mul_f32 v[204:205], v[60:61], v[60:61]
	v_pk_mul_f32 v[206:207], v[62:63], v[62:63]
	v_pk_mul_f32 v[208:209], v[64:65], v[64:65]
	v_add_f32_e32 v229, v98, v99
	v_add_f32_e32 v230, v102, v103
	v_add_f32_e32 v231, v106, v107
	v_add_f32_e32 v232, v110, v111
	v_add_f32_e32 v233, v114, v115
	v_add_f32_e32 v234, v118, v119
	v_add_f32_e32 v235, v122, v123
	v_add_f32_e32 v236, v126, v127
	v_add_f32_e32 v237, v178, v179
	v_add_f32_e32 v238, v182, v183
	v_add_f32_e32 v239, v186, v187
	v_add_f32_e32 v240, v190, v191
	v_add_f32_e32 v241, v194, v195
	v_add_f32_e32 v242, v198, v199
	v_add_f32_e32 v243, v202, v203
	v_add_f32_e32 v244, v206, v207
	v_add_f32_e32 v229, v229, v100
	v_add_f32_e32 v230, v230, v104
	v_add_f32_e32 v231, v231, v108
	v_add_f32_e32 v232, v232, v112
	v_add_f32_e32 v233, v233, v116
	v_add_f32_e32 v234, v234, v120
	v_add_f32_e32 v235, v235, v124
	v_add_f32_e32 v236, v236, v128
	v_add_f32_e32 v237, v237, v180
	v_add_f32_e32 v238, v238, v184
	v_add_f32_e32 v239, v239, v188
	v_add_f32_e32 v240, v240, v192
	v_add_f32_e32 v241, v241, v196
	v_add_f32_e32 v242, v242, v200
	v_add_f32_e32 v243, v243, v204
	v_add_f32_e32 v244, v244, v208
	v_add_f32_e32 v229, v229, v101
	v_add_f32_e32 v230, v230, v105
	v_add_f32_e32 v231, v231, v109
	v_add_f32_e32 v232, v232, v113
	v_add_f32_e32 v233, v233, v117
	v_add_f32_e32 v234, v234, v121
	v_add_f32_e32 v235, v235, v125
	v_add_f32_e32 v236, v236, v129
	v_add_f32_e32 v237, v237, v181
	v_add_f32_e32 v238, v238, v185
	v_add_f32_e32 v239, v239, v189
	v_add_f32_e32 v240, v240, v193
	v_add_f32_e32 v241, v241, v197
	v_add_f32_e32 v242, v242, v201
	v_add_f32_e32 v243, v243, v205
	v_add_f32_e32 v244, v244, v209
	v_pk_mul_f32 v[2:3], v[2:3], v[214:215]
	v_pk_mul_f32 v[4:5], v[4:5], v[216:217]
	v_pk_mul_f32 v[6:7], v[6:7], v[214:215]
	v_pk_mul_f32 v[8:9], v[8:9], v[216:217]
	v_pk_mul_f32 v[10:11], v[10:11], v[214:215]
	v_pk_mul_f32 v[12:13], v[12:13], v[216:217]
	v_pk_mul_f32 v[14:15], v[14:15], v[214:215]
	v_pk_mul_f32 v[16:17], v[16:17], v[216:217]
	v_pk_mul_f32 v[18:19], v[18:19], v[214:215]
	v_pk_mul_f32 v[20:21], v[20:21], v[216:217]
	v_pk_mul_f32 v[22:23], v[22:23], v[214:215]
	v_pk_mul_f32 v[24:25], v[24:25], v[216:217]
	v_pk_mul_f32 v[26:27], v[26:27], v[214:215]
	v_pk_mul_f32 v[28:29], v[28:29], v[216:217]
	v_pk_mul_f32 v[30:31], v[30:31], v[214:215]
	v_pk_mul_f32 v[32:33], v[32:33], v[216:217]
	v_pk_mul_f32 v[34:35], v[34:35], v[214:215]
	v_pk_mul_f32 v[36:37], v[36:37], v[216:217]
	v_pk_mul_f32 v[38:39], v[38:39], v[214:215]
	v_pk_mul_f32 v[40:41], v[40:41], v[216:217]
	v_pk_mul_f32 v[42:43], v[42:43], v[214:215]
	v_pk_mul_f32 v[44:45], v[44:45], v[216:217]
	v_pk_mul_f32 v[46:47], v[46:47], v[214:215]
	v_pk_mul_f32 v[48:49], v[48:49], v[216:217]
	v_pk_mul_f32 v[50:51], v[50:51], v[214:215]
	v_pk_mul_f32 v[52:53], v[52:53], v[216:217]
	v_pk_mul_f32 v[54:55], v[54:55], v[214:215]
	v_pk_mul_f32 v[56:57], v[56:57], v[216:217]
	v_pk_mul_f32 v[58:59], v[58:59], v[214:215]
	v_pk_mul_f32 v[60:61], v[60:61], v[216:217]
	v_pk_mul_f32 v[62:63], v[62:63], v[214:215]
	v_pk_mul_f32 v[64:65], v[64:65], v[216:217]
	v_cvt_pk_bf16_f32 v98, v2, v3
	v_cvt_pk_bf16_f32 v99, v4, v5
	v_cvt_pk_bf16_f32 v102, v6, v7
	v_cvt_pk_bf16_f32 v103, v8, v9
	v_cvt_pk_bf16_f32 v106, v10, v11
	v_cvt_pk_bf16_f32 v107, v12, v13
	v_cvt_pk_bf16_f32 v110, v14, v15
	v_cvt_pk_bf16_f32 v111, v16, v17
	v_cvt_pk_bf16_f32 v114, v18, v19
	v_cvt_pk_bf16_f32 v115, v20, v21
	v_cvt_pk_bf16_f32 v118, v22, v23
	v_cvt_pk_bf16_f32 v119, v24, v25
	v_cvt_pk_bf16_f32 v122, v26, v27
	v_cvt_pk_bf16_f32 v123, v28, v29
	v_cvt_pk_bf16_f32 v126, v30, v31
	v_cvt_pk_bf16_f32 v127, v32, v33
	v_cvt_pk_bf16_f32 v178, v34, v35
	v_cvt_pk_bf16_f32 v179, v36, v37
	v_cvt_pk_bf16_f32 v182, v38, v39
	v_cvt_pk_bf16_f32 v183, v40, v41
	v_cvt_pk_bf16_f32 v186, v42, v43
	v_cvt_pk_bf16_f32 v187, v44, v45
	v_cvt_pk_bf16_f32 v190, v46, v47
	v_cvt_pk_bf16_f32 v191, v48, v49
	v_cvt_pk_bf16_f32 v194, v50, v51
	v_cvt_pk_bf16_f32 v195, v52, v53
	v_cvt_pk_bf16_f32 v198, v54, v55
	v_cvt_pk_bf16_f32 v199, v56, v57
	v_cvt_pk_bf16_f32 v202, v58, v59
	v_cvt_pk_bf16_f32 v203, v60, v61
	v_cvt_pk_bf16_f32 v206, v62, v63
	v_cvt_pk_bf16_f32 v207, v64, v65
	v_readlane_b32 s56, v248, 13
	v_readlane_b32 s57, v248, 14
	s_mul_i32 s0, s51, 0xa000
	s_lshl_b32 s1, s2, 2
	s_add_i32 s0, s0, s1
	s_add_u32 s56, s56, s0
	s_addc_u32 s57, s57, 0
	s_mul_i32 s0, s2, 0x880
	s_add_u32 s58, s8, s0
	s_addc_u32 s59, s9, 0
	v_mov_b32_e32 v228, v224
	global_store_dwordx2 v228, v[98:99], s[58:59] sc0 sc1
	v_add_u32_e32 v228, 0x4400, v228
	global_store_dwordx2 v228, v[102:103], s[58:59] sc0 sc1
	v_add_u32_e32 v228, 0x4400, v228
	global_store_dwordx2 v228, v[106:107], s[58:59] sc0 sc1
	v_add_u32_e32 v228, 0x4400, v228
	global_store_dwordx2 v228, v[110:111], s[58:59] sc0 sc1
	v_add_u32_e32 v228, 0x4400, v228
	global_store_dwordx2 v228, v[114:115], s[58:59] sc0 sc1
	v_add_u32_e32 v228, 0x4400, v228
	global_store_dwordx2 v228, v[118:119], s[58:59] sc0 sc1
	v_add_u32_e32 v228, 0x4400, v228
	global_store_dwordx2 v228, v[122:123], s[58:59] sc0 sc1
	v_add_u32_e32 v228, 0x4400, v228
	global_store_dwordx2 v228, v[126:127], s[58:59] sc0 sc1
	v_add_u32_e32 v228, 0x4400, v228
	global_store_dwordx2 v228, v[178:179], s[58:59] sc0 sc1
	v_add_u32_e32 v228, 0x4400, v228
	global_store_dwordx2 v228, v[182:183], s[58:59] sc0 sc1
	v_add_u32_e32 v228, 0x4400, v228
	global_store_dwordx2 v228, v[186:187], s[58:59] sc0 sc1
	v_add_u32_e32 v228, 0x4400, v228
	global_store_dwordx2 v228, v[190:191], s[58:59] sc0 sc1
	v_add_u32_e32 v228, 0x4400, v228
	global_store_dwordx2 v228, v[194:195], s[58:59] sc0 sc1
	v_add_u32_e32 v228, 0x4400, v228
	global_store_dwordx2 v228, v[198:199], s[58:59] sc0 sc1
	v_add_u32_e32 v228, 0x4400, v228
	global_store_dwordx2 v228, v[202:203], s[58:59] sc0 sc1
	v_add_u32_e32 v228, 0x4400, v228
	global_store_dwordx2 v228, v[206:207], s[58:59] sc0 sc1
	v_add_f32_dpp v229, v229, v229 quad_perm:[1,0,3,2] row_mask:0xf bank_mask:0xf
	v_add_f32_dpp v230, v230, v230 quad_perm:[1,0,3,2] row_mask:0xf bank_mask:0xf
	v_add_f32_dpp v231, v231, v231 quad_perm:[1,0,3,2] row_mask:0xf bank_mask:0xf
	v_add_f32_dpp v232, v232, v232 quad_perm:[1,0,3,2] row_mask:0xf bank_mask:0xf
	v_add_f32_dpp v233, v233, v233 quad_perm:[1,0,3,2] row_mask:0xf bank_mask:0xf
	v_add_f32_dpp v234, v234, v234 quad_perm:[1,0,3,2] row_mask:0xf bank_mask:0xf
	v_add_f32_dpp v235, v235, v235 quad_perm:[1,0,3,2] row_mask:0xf bank_mask:0xf
	v_add_f32_dpp v236, v236, v236 quad_perm:[1,0,3,2] row_mask:0xf bank_mask:0xf
	v_add_f32_dpp v237, v237, v237 quad_perm:[1,0,3,2] row_mask:0xf bank_mask:0xf
	v_add_f32_dpp v238, v238, v238 quad_perm:[1,0,3,2] row_mask:0xf bank_mask:0xf
	v_add_f32_dpp v239, v239, v239 quad_perm:[1,0,3,2] row_mask:0xf bank_mask:0xf
	v_add_f32_dpp v240, v240, v240 quad_perm:[1,0,3,2] row_mask:0xf bank_mask:0xf
	v_add_f32_dpp v241, v241, v241 quad_perm:[1,0,3,2] row_mask:0xf bank_mask:0xf
	v_add_f32_dpp v242, v242, v242 quad_perm:[1,0,3,2] row_mask:0xf bank_mask:0xf
	v_add_f32_dpp v243, v243, v243 quad_perm:[1,0,3,2] row_mask:0xf bank_mask:0xf
	v_add_f32_dpp v244, v244, v244 quad_perm:[1,0,3,2] row_mask:0xf bank_mask:0xf
	v_add_f32_dpp v229, v229, v229 quad_perm:[2,3,0,1] row_mask:0xf bank_mask:0xf
	v_add_f32_dpp v230, v230, v230 quad_perm:[2,3,0,1] row_mask:0xf bank_mask:0xf
	v_add_f32_dpp v231, v231, v231 quad_perm:[2,3,0,1] row_mask:0xf bank_mask:0xf
	v_add_f32_dpp v232, v232, v232 quad_perm:[2,3,0,1] row_mask:0xf bank_mask:0xf
	v_add_f32_dpp v233, v233, v233 quad_perm:[2,3,0,1] row_mask:0xf bank_mask:0xf
	v_add_f32_dpp v234, v234, v234 quad_perm:[2,3,0,1] row_mask:0xf bank_mask:0xf
	v_add_f32_dpp v235, v235, v235 quad_perm:[2,3,0,1] row_mask:0xf bank_mask:0xf
	v_add_f32_dpp v236, v236, v236 quad_perm:[2,3,0,1] row_mask:0xf bank_mask:0xf
	v_add_f32_dpp v237, v237, v237 quad_perm:[2,3,0,1] row_mask:0xf bank_mask:0xf
	v_add_f32_dpp v238, v238, v238 quad_perm:[2,3,0,1] row_mask:0xf bank_mask:0xf
	v_add_f32_dpp v239, v239, v239 quad_perm:[2,3,0,1] row_mask:0xf bank_mask:0xf
	v_add_f32_dpp v240, v240, v240 quad_perm:[2,3,0,1] row_mask:0xf bank_mask:0xf
	v_add_f32_dpp v241, v241, v241 quad_perm:[2,3,0,1] row_mask:0xf bank_mask:0xf
	v_add_f32_dpp v242, v242, v242 quad_perm:[2,3,0,1] row_mask:0xf bank_mask:0xf
	v_add_f32_dpp v243, v243, v243 quad_perm:[2,3,0,1] row_mask:0xf bank_mask:0xf
	v_add_f32_dpp v244, v244, v244 quad_perm:[2,3,0,1] row_mask:0xf bank_mask:0xf
	v_add_f32_dpp v229, v229, v229 row_ror:4 row_mask:0xf bank_mask:0xf
	v_add_f32_dpp v230, v230, v230 row_ror:4 row_mask:0xf bank_mask:0xf
	v_add_f32_dpp v231, v231, v231 row_ror:4 row_mask:0xf bank_mask:0xf
	v_add_f32_dpp v232, v232, v232 row_ror:4 row_mask:0xf bank_mask:0xf
	v_add_f32_dpp v233, v233, v233 row_ror:4 row_mask:0xf bank_mask:0xf
	v_add_f32_dpp v234, v234, v234 row_ror:4 row_mask:0xf bank_mask:0xf
	v_add_f32_dpp v235, v235, v235 row_ror:4 row_mask:0xf bank_mask:0xf
	v_add_f32_dpp v236, v236, v236 row_ror:4 row_mask:0xf bank_mask:0xf
	v_add_f32_dpp v237, v237, v237 row_ror:4 row_mask:0xf bank_mask:0xf
	v_add_f32_dpp v238, v238, v238 row_ror:4 row_mask:0xf bank_mask:0xf
	v_add_f32_dpp v239, v239, v239 row_ror:4 row_mask:0xf bank_mask:0xf
	v_add_f32_dpp v240, v240, v240 row_ror:4 row_mask:0xf bank_mask:0xf
	v_add_f32_dpp v241, v241, v241 row_ror:4 row_mask:0xf bank_mask:0xf
	v_add_f32_dpp v242, v242, v242 row_ror:4 row_mask:0xf bank_mask:0xf
	v_add_f32_dpp v243, v243, v243 row_ror:4 row_mask:0xf bank_mask:0xf
	v_add_f32_dpp v244, v244, v244 row_ror:4 row_mask:0xf bank_mask:0xf
	v_add_f32_dpp v229, v229, v229 row_ror:8 row_mask:0xf bank_mask:0xf
	v_add_f32_dpp v230, v230, v230 row_ror:8 row_mask:0xf bank_mask:0xf
	v_add_f32_dpp v231, v231, v231 row_ror:8 row_mask:0xf bank_mask:0xf
	v_add_f32_dpp v232, v232, v232 row_ror:8 row_mask:0xf bank_mask:0xf
	v_add_f32_dpp v233, v233, v233 row_ror:8 row_mask:0xf bank_mask:0xf
	v_add_f32_dpp v234, v234, v234 row_ror:8 row_mask:0xf bank_mask:0xf
	v_add_f32_dpp v235, v235, v235 row_ror:8 row_mask:0xf bank_mask:0xf
	v_add_f32_dpp v236, v236, v236 row_ror:8 row_mask:0xf bank_mask:0xf
	v_add_f32_dpp v237, v237, v237 row_ror:8 row_mask:0xf bank_mask:0xf
	v_add_f32_dpp v238, v238, v238 row_ror:8 row_mask:0xf bank_mask:0xf
	v_add_f32_dpp v239, v239, v239 row_ror:8 row_mask:0xf bank_mask:0xf
	v_add_f32_dpp v240, v240, v240 row_ror:8 row_mask:0xf bank_mask:0xf
	v_add_f32_dpp v241, v241, v241 row_ror:8 row_mask:0xf bank_mask:0xf
	v_add_f32_dpp v242, v242, v242 row_ror:8 row_mask:0xf bank_mask:0xf
	v_add_f32_dpp v243, v243, v243 row_ror:8 row_mask:0xf bank_mask:0xf
	v_add_f32_dpp v244, v244, v244 row_ror:8 row_mask:0xf bank_mask:0xf
	v_add_f32_dpp v229, v229, v229 row_bcast:15 row_mask:0xa bank_mask:0xf
	v_add_f32_dpp v230, v230, v230 row_bcast:15 row_mask:0xa bank_mask:0xf
	v_add_f32_dpp v231, v231, v231 row_bcast:15 row_mask:0xa bank_mask:0xf
	v_add_f32_dpp v232, v232, v232 row_bcast:15 row_mask:0xa bank_mask:0xf
	v_add_f32_dpp v233, v233, v233 row_bcast:15 row_mask:0xa bank_mask:0xf
	v_add_f32_dpp v234, v234, v234 row_bcast:15 row_mask:0xa bank_mask:0xf
	v_add_f32_dpp v235, v235, v235 row_bcast:15 row_mask:0xa bank_mask:0xf
	v_add_f32_dpp v236, v236, v236 row_bcast:15 row_mask:0xa bank_mask:0xf
	v_add_f32_dpp v237, v237, v237 row_bcast:15 row_mask:0xa bank_mask:0xf
	v_add_f32_dpp v238, v238, v238 row_bcast:15 row_mask:0xa bank_mask:0xf
	v_add_f32_dpp v239, v239, v239 row_bcast:15 row_mask:0xa bank_mask:0xf
	v_add_f32_dpp v240, v240, v240 row_bcast:15 row_mask:0xa bank_mask:0xf
	v_add_f32_dpp v241, v241, v241 row_bcast:15 row_mask:0xa bank_mask:0xf
	v_add_f32_dpp v242, v242, v242 row_bcast:15 row_mask:0xa bank_mask:0xf
	v_add_f32_dpp v243, v243, v243 row_bcast:15 row_mask:0xa bank_mask:0xf
	v_add_f32_dpp v244, v244, v244 row_bcast:15 row_mask:0xa bank_mask:0xf
	s_mov_b64 s[40:41], exec
	s_mov_b32 s0, 0x80000000
	s_mov_b32 s1, 0x80000000
	s_mov_b64 exec, s[0:1]
	global_store_dword v226, v229, s[56:57]
	global_store_dword v226, v230, s[56:57] offset:32
	global_store_dword v226, v231, s[56:57] offset:64
	global_store_dword v226, v232, s[56:57] offset:96
	global_store_dword v226, v233, s[56:57] offset:128
	global_store_dword v226, v234, s[56:57] offset:160
	global_store_dword v226, v235, s[56:57] offset:192
	global_store_dword v226, v236, s[56:57] offset:224
	global_store_dword v226, v237, s[56:57] offset:256
	global_store_dword v226, v238, s[56:57] offset:288
	global_store_dword v226, v239, s[56:57] offset:320
	global_store_dword v226, v240, s[56:57] offset:352
	global_store_dword v226, v241, s[56:57] offset:384
	global_store_dword v226, v242, s[56:57] offset:416
	global_store_dword v226, v243, s[56:57] offset:448
	global_store_dword v226, v244, s[56:57] offset:480
	s_mov_b64 exec, s[40:41]
	s_branch .LBB0_122

.Ltail_165:
	ds_read_b128 v[98:101], v138
	ds_read_b128 v[102:105], v139 offset:36864
	ds_read_b128 v[106:109], v138 offset:32
	ds_read_b128 v[110:113], v139 offset:36896
	ds_read_b128 v[114:117], v139 offset:41472
	ds_read_b128 v[118:121], v138 offset:4608
	ds_read_b128 v[122:125], v138 offset:4640
	s_waitcnt vmcnt(0)
	ds_read_b128 v[126:129], v139 offset:41504
	ds_write_b128 v199, v[94:97] offset:18432
	s_waitcnt lgkmcnt(7)
	v_mfma_f32_32x32x16_bf16 v[50:65], v[98:101], v[102:105], v[50:65]
	s_waitcnt lgkmcnt(4)
	v_mfma_f32_32x32x16_bf16 v[34:49], v[98:101], v[114:117], v[34:49]
	s_waitcnt lgkmcnt(3)
	v_mfma_f32_32x32x16_bf16 v[18:33], v[118:121], v[102:105], v[18:33]
	ds_write_b128 v199, v[90:93] offset:55296
	v_mfma_f32_32x32x16_bf16 v[2:17], v[118:121], v[114:117], v[2:17]
	ds_read_b128 v[90:93], v138 offset:64
	ds_read_b128 v[94:97], v138 offset:4672
	ds_read_b128 v[98:101], v139 offset:36928
	ds_read_b128 v[102:105], v139 offset:41536
	v_mfma_f32_32x32x16_bf16 v[50:65], v[106:109], v[110:113], v[50:65]
	ds_write_b128 v199, v[86:89] offset:23040
	s_waitcnt lgkmcnt(7)
	v_mfma_f32_32x32x16_bf16 v[34:49], v[106:109], v[126:129], v[34:49]
	v_mfma_f32_32x32x16_bf16 v[18:33], v[122:125], v[110:113], v[18:33]
	ds_write_b128 v199, v[82:85] offset:59904
	v_mfma_f32_32x32x16_bf16 v[2:17], v[122:125], v[126:129], v[2:17]
	ds_read_b128 v[82:85], v138 offset:96
	ds_read_b128 v[86:89], v138 offset:4704
	ds_read_b128 v[106:109], v139 offset:36960
	ds_read_b128 v[110:113], v139 offset:41568
	s_waitcnt lgkmcnt(7)
	v_mfma_f32_32x32x16_bf16 v[50:65], v[90:93], v[98:101], v[50:65]
	ds_write_b128 v199, v[78:81] offset:27648
	s_waitcnt lgkmcnt(7)
	v_mfma_f32_32x32x16_bf16 v[34:49], v[90:93], v[102:105], v[34:49]
	v_mfma_f32_32x32x16_bf16 v[18:33], v[94:97], v[98:101], v[18:33]
	ds_write_b128 v199, v[74:77] offset:64512
	v_mfma_f32_32x32x16_bf16 v[2:17], v[94:97], v[102:105], v[2:17]
	s_waitcnt lgkmcnt(3)
	v_mfma_f32_32x32x16_bf16 v[50:65], v[82:85], v[106:109], v[50:65]
	ds_write_b128 v199, v[70:73] offset:32256
	s_waitcnt lgkmcnt(3)
	v_mfma_f32_32x32x16_bf16 v[34:49], v[82:85], v[110:113], v[34:49]
	v_mfma_f32_32x32x16_bf16 v[18:33], v[86:89], v[106:109], v[18:33]
	ds_write_b128 v202, v[66:69] offset:13824
	v_mfma_f32_32x32x16_bf16 v[2:17], v[86:89], v[110:113], v[2:17]
	s_waitcnt lgkmcnt(0)
	s_barrier
	ds_read_b128 v[66:69], v138 offset:18432
	ds_read_b128 v[70:73], v139 offset:55296
	ds_read_b128 v[74:77], v138 offset:18464
	ds_read_b128 v[78:81], v139 offset:55328
	ds_read_b128 v[82:85], v139 offset:59904
	ds_read_b128 v[86:89], v138 offset:23040
	ds_read_b128 v[90:93], v138 offset:23072
	ds_read_b128 v[94:97], v139 offset:59936
	s_waitcnt lgkmcnt(6)
	v_mfma_f32_32x32x16_bf16 v[50:65], v[66:69], v[70:73], v[50:65]
	s_waitcnt lgkmcnt(3)
	v_mfma_f32_32x32x16_bf16 v[34:49], v[66:69], v[82:85], v[34:49]
	s_waitcnt lgkmcnt(2)
	v_mfma_f32_32x32x16_bf16 v[18:33], v[86:89], v[70:73], v[18:33]
	v_mfma_f32_32x32x16_bf16 v[2:17], v[86:89], v[82:85], v[2:17]
	ds_read_b128 v[66:69], v138 offset:18496
	ds_read_b128 v[70:73], v138 offset:23104
	ds_read_b128 v[82:85], v139 offset:55360
	ds_read_b128 v[86:89], v139 offset:59968
	v_mfma_f32_32x32x16_bf16 v[50:65], v[74:77], v[78:81], v[50:65]
	s_waitcnt lgkmcnt(4)
	v_mfma_f32_32x32x16_bf16 v[34:49], v[74:77], v[94:97], v[34:49]
	v_mfma_f32_32x32x16_bf16 v[18:33], v[90:93], v[78:81], v[18:33]
	v_mfma_f32_32x32x16_bf16 v[2:17], v[90:93], v[94:97], v[2:17]
	ds_read_b128 v[74:77], v138 offset:18528
	ds_read_b128 v[78:81], v138 offset:23136
	ds_read_b128 v[90:93], v139 offset:55392
	ds_read_b128 v[94:97], v139 offset:60000
	s_waitcnt lgkmcnt(5)
	v_mfma_f32_32x32x16_bf16 v[50:65], v[66:69], v[82:85], v[50:65]
	s_waitcnt lgkmcnt(4)
	v_mfma_f32_32x32x16_bf16 v[34:49], v[66:69], v[86:89], v[34:49]
	v_mfma_f32_32x32x16_bf16 v[18:33], v[70:73], v[82:85], v[18:33]
	v_mfma_f32_32x32x16_bf16 v[2:17], v[70:73], v[86:89], v[2:17]
	s_waitcnt lgkmcnt(1)
	v_mfma_f32_32x32x16_bf16 v[50:65], v[74:77], v[90:93], v[50:65]
	s_waitcnt lgkmcnt(0)
	v_mfma_f32_32x32x16_bf16 v[34:49], v[74:77], v[94:97], v[34:49]
	v_mfma_f32_32x32x16_bf16 v[18:33], v[78:81], v[90:93], v[18:33]
	v_mfma_f32_32x32x16_bf16 v[2:17], v[78:81], v[94:97], v[2:17]
	v_lshl_or_b32 v66, v198, 2, v201
	s_movk_i32 s0, 0x210
	v_and_or_b32 v67, v137, 64, v151
	v_mul_lo_u32 v66, v66, s0
	v_lshl_add_u32 v66, v67, 2, v66
	s_barrier
	s_nop 3
	ds_write2_b32 v66, v50, v34 offset1:32
	ds_write2_b32 v66, v51, v35 offset0:132 offset1:164
	v_add_u32_e32 v34, 0x400, v66
	ds_write2_b32 v34, v52, v36 offset0:8 offset1:40
	ds_write2_b32 v34, v53, v37 offset0:140 offset1:172
	v_add_u32_e32 v34, 0x1000, v66
	ds_write2_b32 v34, v54, v38 offset0:32 offset1:64
	ds_write2_b32 v34, v55, v39 offset0:164 offset1:196
	v_add_u32_e32 v34, 0x1400, v66
	ds_write2_b32 v34, v56, v40 offset0:40 offset1:72
	ds_write2_b32 v34, v57, v41 offset0:172 offset1:204
	v_add_u32_e32 v34, 0x2000, v66
	ds_write2_b32 v34, v58, v42 offset0:64 offset1:96
	ds_write2_b32 v34, v59, v43 offset0:196 offset1:228
	v_add_u32_e32 v34, 0x2400, v66
	ds_write2_b32 v34, v60, v44 offset0:72 offset1:104
	ds_write2_b32 v34, v61, v45 offset0:204 offset1:236
	v_add_u32_e32 v34, 0x3000, v66
	ds_write2_b32 v34, v62, v46 offset0:96 offset1:128
	v_add_u32_e32 v34, 0x3200, v66
	ds_write2_b32 v34, v63, v47 offset0:100 offset1:132
	v_add_u32_e32 v34, 0x3400, v66
	ds_write2_b32 v34, v64, v48 offset0:104 offset1:136
	v_add_u32_e32 v34, 0x3600, v66
	ds_write2_b32 v34, v65, v49 offset0:108 offset1:140
	v_add_u32_e32 v34, 0x4000, v66
	ds_write2_b32 v34, v18, v2 offset0:128 offset1:160
	v_add_u32_e32 v2, 0x4400, v66
	ds_write2_b32 v2, v19, v3 offset0:4 offset1:36
	ds_write2_b32 v2, v20, v4 offset0:136 offset1:168
	v_add_u32_e32 v2, 0x4800, v66
	ds_write2_b32 v2, v21, v5 offset0:12 offset1:44
	v_add_u32_e32 v2, 0x5000, v66
	ds_write2_b32 v2, v22, v6 offset0:160 offset1:192
	v_add_u32_e32 v2, 0x5400, v66
	ds_write2_b32 v2, v23, v7 offset0:36 offset1:68
	ds_write2_b32 v2, v24, v8 offset0:168 offset1:200
	v_add_u32_e32 v2, 0x5800, v66
	ds_write2_b32 v2, v25, v9 offset0:44 offset1:76
	v_add_u32_e32 v2, 0x6000, v66
	ds_write2_b32 v2, v26, v10 offset0:192 offset1:224
	v_add_u32_e32 v2, 0x6400, v66
	ds_write2_b32 v2, v27, v11 offset0:68 offset1:100
	ds_write2_b32 v2, v28, v12 offset0:200 offset1:232
	v_add_u32_e32 v2, 0x6800, v66
	ds_write2_b32 v2, v29, v13 offset0:76 offset1:108
	v_add_u32_e32 v2, 0x7200, v66
	ds_write2_b32 v2, v30, v14 offset0:96 offset1:128
	v_add_u32_e32 v2, 0x7400, v66
	ds_write2_b32 v2, v31, v15 offset0:100 offset1:132
	v_add_u32_e32 v2, 0x7600, v66
	ds_write2_b32 v2, v32, v16 offset0:104 offset1:136
	v_add_u32_e32 v2, 0x7800, v66
	s_cmp_lg_u32 s96, 0
	s_mov_b64 s[0:1], -1
	ds_write2_b32 v2, v33, v17 offset0:108 offset1:140
	s_waitcnt lgkmcnt(0)
	s_barrier
	ds_write_b32 v140, v135
	s_waitcnt lgkmcnt(0)
	s_barrier
	s_cbranch_scc0 .LBB0_168
	v_add_u32_e32 v2, s55, v141
	v_ashrrev_i32_e32 v3, 31, v2
	v_lshlrev_b64 v[2:3], 11, v[2:3]
	v_lshl_add_u64 v[2:3], s[10:11], 0, v[2:3]
	s_lshl_b32 s96, s51, 1
	v_lshl_add_u64 v[2:3], v[2:3], 0, s[96:97]
	v_mov_b32_e32 v135, v147
	v_or_b32_e32 v13, 0x10a00, v142
	ds_read_b32 v12, v143
	v_lshl_add_u64 v[26:27], v[2:3], 0, v[134:135]
	ds_read_b128 v[2:5], v197
	ds_read_b128 v[6:9], v197 offset:16
	ds_read_b128 v[14:17], v197 offset:32
	ds_read_b128 v[18:21], v197 offset:48
	ds_read_b128 v[22:25], v13
	s_mov_b64 s[0:1], 0x283f800
	v_lshl_add_u64 v[10:11], v[26:27], 0, s[0:1]
	s_waitcnt lgkmcnt(0)
	v_pk_fma_f32 v[2:3], v[2:3], v[12:13], v[22:23] op_sel_hi:[1,0,1]
	s_nop 0
	v_mul_f32_e32 v13, 0xbfb8aa3b, v2
	v_exp_f32_e32 v22, v13
	v_mul_f32_e32 v13, 0xbfb8aa3b, v3
	v_exp_f32_e32 v23, v13
	s_nop 0
	v_pk_add_f32 v[22:23], v[22:23], 1.0 op_sel_hi:[1,0]
	s_nop 0
	v_rcp_f32_e32 v28, v23
	s_nop 0
	v_mul_f32_e32 v30, v3, v28
	v_fma_f32 v31, -v23, v30, v3
	v_fma_f32 v13, v31, v28, v30
	v_div_fixup_f32 v3, v13, v23, v3
	v_rcp_f32_e32 v23, v22
	s_nop 0
	v_mul_f32_e32 v29, v2, v23
	v_fma_f32 v30, -v22, v29, v2
	v_fma_f32 v13, v30, v23, v29
	v_div_fixup_f32 v2, v13, v22, v2
	v_pk_fma_f32 v[4:5], v[4:5], v[12:13], v[24:25] op_sel_hi:[1,0,1]
	v_cvt_pk_bf16_f32 v2, v2, v3
	v_mul_f32_e32 v3, 0xbfb8aa3b, v4
	v_exp_f32_e32 v22, v3
	v_mul_f32_e32 v3, 0xbfb8aa3b, v5
	v_exp_f32_e32 v23, v3
	s_nop 0
	v_pk_add_f32 v[22:23], v[22:23], 1.0 op_sel_hi:[1,0]
	s_nop 0
	v_rcp_f32_e32 v13, v23
	s_nop 0
	v_mul_f32_e32 v25, v5, v13
	v_fma_f32 v28, -v23, v25, v5
	v_fma_f32 v3, v28, v13, v25
	v_div_fixup_f32 v3, v3, v23, v5
	v_rcp_f32_e32 v13, v22
	s_nop 0
	v_mul_f32_e32 v24, v4, v13
	v_fma_f32 v25, -v22, v24, v4
	v_fma_f32 v5, v25, v13, v24
	v_div_fixup_f32 v4, v5, v22, v4
	v_cvt_pk_bf16_f32 v3, v4, v3
	v_add_u32_e32 v4, 0x10a10, v142
	ds_read_b128 v[22:25], v4
	s_waitcnt lgkmcnt(0)
	v_pk_fma_f32 v[4:5], v[6:7], v[12:13], v[22:23] op_sel_hi:[1,0,1]
	s_nop 0
	v_mul_f32_e32 v6, 0xbfb8aa3b, v4
	v_mul_f32_e32 v7, 0xbfb8aa3b, v5
	v_exp_f32_e32 v6, v6
	v_exp_f32_e32 v7, v7
	s_nop 0
	v_pk_add_f32 v[6:7], v[6:7], 1.0 op_sel_hi:[1,0]
	s_nop 0
	v_rcp_f32_e32 v22, v7
	s_nop 0
	v_mul_f32_e32 v28, v5, v22
	v_fma_f32 v29, -v7, v28, v5
	v_fma_f32 v13, v29, v22, v28
	v_div_fixup_f32 v5, v13, v7, v5
	v_rcp_f32_e32 v13, v6
	s_nop 0
	v_mul_f32_e32 v23, v4, v13
	v_fma_f32 v28, -v6, v23, v4
	v_fma_f32 v7, v28, v13, v23
	v_div_fixup_f32 v4, v7, v6, v4
	v_pk_fma_f32 v[6:7], v[8:9], v[12:13], v[24:25] op_sel_hi:[1,0,1]
	v_cvt_pk_bf16_f32 v4, v4, v5
	v_mul_f32_e32 v5, 0xbfb8aa3b, v6
	v_exp_f32_e32 v8, v5
	v_mul_f32_e32 v5, 0xbfb8aa3b, v7
	v_exp_f32_e32 v9, v5
	s_nop 0
	v_pk_add_f32 v[8:9], v[8:9], 1.0 op_sel_hi:[1,0]
	s_nop 0
	v_rcp_f32_e32 v13, v9
	s_nop 0
	v_mul_f32_e32 v23, v7, v13
	v_fma_f32 v24, -v9, v23, v7
	v_fma_f32 v5, v24, v13, v23
	v_div_fixup_f32 v5, v5, v9, v7
	v_div_scale_f32 v7, s[0:1], v8, v8, v6
	v_rcp_f32_e32 v9, v7
	s_mov_b32 s0, 0x283f000
	v_fma_f32 v13, -v7, v9, 1.0
	v_fmac_f32_e32 v9, v13, v9
	v_div_scale_f32 v13, vcc, v6, v8, v6
	v_mul_f32_e32 v22, v13, v9
	v_fma_f32 v23, -v7, v22, v13
	v_fmac_f32_e32 v22, v23, v9
	v_fma_f32 v7, -v7, v22, v13
	v_div_fmas_f32 v7, v7, v9, v22
	v_div_fixup_f32 v6, v7, v8, v6
	v_cvt_pk_bf16_f32 v5, v6, v5
	v_add_co_u32_e32 v6, vcc, s0, v26
	s_nop 1
	v_addc_co_u32_e32 v7, vcc, 0, v27, vcc
	global_store_dwordx4 v[6:7], v[2:5], off offset:2048
	s_nop 1
	v_add_u32_e32 v2, 0x10a20, v142
	ds_read_b128 v[2:5], v2
	s_waitcnt lgkmcnt(0)
	v_pk_fma_f32 v[2:3], v[14:15], v[12:13], v[2:3] op_sel_hi:[1,0,1]
	s_nop 0
	v_mul_f32_e32 v6, 0xbfb8aa3b, v2
	v_mul_f32_e32 v7, 0xbfb8aa3b, v3
	v_exp_f32_e32 v6, v6
	v_exp_f32_e32 v7, v7
	s_nop 0
	v_pk_add_f32 v[6:7], v[6:7], 1.0 op_sel_hi:[1,0]
	s_nop 0
	v_rcp_f32_e32 v9, v7
	s_nop 0
	v_mul_f32_e32 v14, v3, v9
	v_fma_f32 v15, -v7, v14, v3
	v_fma_f32 v8, v15, v9, v14
	v_div_fixup_f32 v3, v8, v7, v3
	v_rcp_f32_e32 v8, v6
	s_nop 0
	v_mul_f32_e32 v13, v2, v8
	v_fma_f32 v14, -v6, v13, v2
	v_fma_f32 v7, v14, v8, v13
	v_div_fixup_f32 v2, v7, v6, v2
	v_pk_fma_f32 v[4:5], v[16:17], v[12:13], v[4:5] op_sel_hi:[1,0,1]
	v_cvt_pk_bf16_f32 v2, v2, v3
	v_mul_f32_e32 v3, 0xbfb8aa3b, v4
	v_exp_f32_e32 v6, v3
	v_mul_f32_e32 v3, 0xbfb8aa3b, v5
	v_exp_f32_e32 v7, v3
	s_nop 0
	v_pk_add_f32 v[6:7], v[6:7], 1.0 op_sel_hi:[1,0]
	s_nop 0
	v_rcp_f32_e32 v8, v7
	s_nop 0
	v_mul_f32_e32 v13, v5, v8
	v_fma_f32 v14, -v7, v13, v5
	v_fma_f32 v3, v14, v8, v13
	v_div_fixup_f32 v3, v3, v7, v5
	v_rcp_f32_e32 v7, v6
	s_nop 0
	v_mul_f32_e32 v9, v4, v7
	v_fma_f32 v13, -v6, v9, v4
	v_fma_f32 v5, v13, v7, v9
	v_div_fixup_f32 v4, v5, v6, v4
	v_cvt_pk_bf16_f32 v3, v4, v3
	v_add_u32_e32 v4, 0x10a30, v142
	ds_read_b128 v[4:7], v4
	s_waitcnt lgkmcnt(0)
	v_pk_fma_f32 v[4:5], v[18:19], v[12:13], v[4:5] op_sel_hi:[1,0,1]
	s_nop 0
	v_mul_f32_e32 v8, 0xbfb8aa3b, v4
	v_mul_f32_e32 v9, 0xbfb8aa3b, v5
	v_exp_f32_e32 v8, v8
	v_exp_f32_e32 v9, v9
	s_nop 0
	v_pk_add_f32 v[8:9], v[8:9], 1.0 op_sel_hi:[1,0]
	s_nop 0
	v_rcp_f32_e32 v14, v9
	s_nop 0
	v_mul_f32_e32 v16, v5, v14
	v_fma_f32 v17, -v9, v16, v5
	v_fma_f32 v13, v17, v14, v16
	v_div_fixup_f32 v5, v13, v9, v5
	v_rcp_f32_e32 v13, v8
	s_nop 0
	v_mul_f32_e32 v15, v4, v13
	v_fma_f32 v16, -v8, v15, v4
	v_fma_f32 v9, v16, v13, v15
	v_div_fixup_f32 v4, v9, v8, v4
	v_pk_fma_f32 v[6:7], v[20:21], v[12:13], v[6:7] op_sel_hi:[1,0,1]
	v_cvt_pk_bf16_f32 v4, v4, v5
	v_mul_f32_e32 v5, 0xbfb8aa3b, v6
	v_exp_f32_e32 v8, v5
	v_mul_f32_e32 v5, 0xbfb8aa3b, v7
	v_exp_f32_e32 v9, v5
	s_nop 0
	v_pk_add_f32 v[8:9], v[8:9], 1.0 op_sel_hi:[1,0]
	s_nop 0
	v_rcp_f32_e32 v13, v9
	s_nop 0
	v_mul_f32_e32 v15, v7, v13
	v_fma_f32 v16, -v9, v15, v7
	v_fma_f32 v5, v16, v13, v15
	v_div_fixup_f32 v5, v5, v9, v7
	v_rcp_f32_e32 v9, v8
	s_nop 0
	v_mul_f32_e32 v14, v6, v9
	v_fma_f32 v15, -v8, v14, v6
	v_fma_f32 v7, v15, v9, v14
	v_div_fixup_f32 v6, v7, v8, v6
	v_cvt_pk_bf16_f32 v5, v6, v5
	v_add_u32_e32 v6, 0x10a40, v142
	global_store_dwordx4 v[10:11], v[2:5], off offset:16
	ds_read_b128 v[2:5], v197 offset:64
	ds_read_b128 v[6:9], v6
	s_waitcnt lgkmcnt(0)
	v_pk_fma_f32 v[2:3], v[2:3], v[12:13], v[6:7] op_sel_hi:[1,0,1]
	s_nop 0
	v_mul_f32_e32 v6, 0xbfb8aa3b, v2
	v_mul_f32_e32 v7, 0xbfb8aa3b, v3
	v_exp_f32_e32 v6, v6
	v_exp_f32_e32 v7, v7
	s_nop 0
	v_pk_add_f32 v[6:7], v[6:7], 1.0 op_sel_hi:[1,0]
	s_nop 0
	v_rcp_f32_e32 v14, v7
	s_nop 0
	v_mul_f32_e32 v16, v3, v14
	v_fma_f32 v17, -v7, v16, v3
	v_fma_f32 v13, v17, v14, v16
	v_div_fixup_f32 v3, v13, v7, v3
	v_rcp_f32_e32 v13, v6
	s_nop 0
	v_mul_f32_e32 v15, v2, v13
	v_fma_f32 v16, -v6, v15, v2
	v_fma_f32 v7, v16, v13, v15
	v_div_fixup_f32 v2, v7, v6, v2
	v_pk_fma_f32 v[4:5], v[4:5], v[12:13], v[8:9] op_sel_hi:[1,0,1]
	v_cvt_pk_bf16_f32 v2, v2, v3
	v_mul_f32_e32 v3, 0xbfb8aa3b, v4
	v_exp_f32_e32 v6, v3
	v_mul_f32_e32 v3, 0xbfb8aa3b, v5
	v_exp_f32_e32 v7, v3
	s_nop 0
	v_pk_add_f32 v[6:7], v[6:7], 1.0 op_sel_hi:[1,0]
	s_nop 0
	v_rcp_f32_e32 v8, v7
	s_nop 0
	v_mul_f32_e32 v13, v5, v8
	v_fma_f32 v14, -v7, v13, v5
	v_fma_f32 v3, v14, v8, v13
	v_div_fixup_f32 v3, v3, v7, v5
	v_rcp_f32_e32 v7, v6
	s_nop 0
	v_mul_f32_e32 v9, v4, v7
	v_fma_f32 v13, -v6, v9, v4
	v_fma_f32 v5, v13, v7, v9
	v_div_fixup_f32 v4, v5, v6, v4
	v_add_u32_e32 v8, 0x10a50, v142
	v_cvt_pk_bf16_f32 v3, v4, v3
	ds_read_b128 v[4:7], v197 offset:80
	ds_read_b128 v[14:17], v8
	s_waitcnt lgkmcnt(0)
	v_pk_fma_f32 v[4:5], v[4:5], v[12:13], v[14:15] op_sel_hi:[1,0,1]
	s_nop 0
	v_mul_f32_e32 v8, 0xbfb8aa3b, v4
	v_mul_f32_e32 v9, 0xbfb8aa3b, v5
	v_exp_f32_e32 v8, v8
	v_exp_f32_e32 v9, v9
	s_nop 0
	v_pk_add_f32 v[8:9], v[8:9], 1.0 op_sel_hi:[1,0]
	s_nop 0
	v_rcp_f32_e32 v14, v9
	s_nop 0
	v_mul_f32_e32 v18, v5, v14
	v_fma_f32 v19, -v9, v18, v5
	v_fma_f32 v13, v19, v14, v18
	v_div_fixup_f32 v5, v13, v9, v5
	v_rcp_f32_e32 v13, v8
	s_nop 0
	v_mul_f32_e32 v15, v4, v13
	v_fma_f32 v18, -v8, v15, v4
	v_fma_f32 v9, v18, v13, v15
	v_div_fixup_f32 v4, v9, v8, v4
	v_pk_fma_f32 v[6:7], v[6:7], v[12:13], v[16:17] op_sel_hi:[1,0,1]
	v_cvt_pk_bf16_f32 v4, v4, v5
	v_mul_f32_e32 v5, 0xbfb8aa3b, v6
	v_exp_f32_e32 v8, v5
	v_mul_f32_e32 v5, 0xbfb8aa3b, v7
	v_exp_f32_e32 v9, v5
	s_nop 0
	v_pk_add_f32 v[8:9], v[8:9], 1.0 op_sel_hi:[1,0]
	s_nop 0
	v_rcp_f32_e32 v13, v9
	s_nop 0
	v_mul_f32_e32 v15, v7, v13
	v_fma_f32 v16, -v9, v15, v7
	v_fma_f32 v5, v16, v13, v15
	v_div_fixup_f32 v5, v5, v9, v7
	v_rcp_f32_e32 v9, v8
	s_nop 0
	v_mul_f32_e32 v14, v6, v9
	v_fma_f32 v15, -v8, v14, v6
	v_fma_f32 v7, v15, v9, v14
	v_div_fixup_f32 v6, v7, v8, v6
	v_cvt_pk_bf16_f32 v5, v6, v5
	global_store_dwordx4 v[10:11], v[2:5], off offset:32
	v_add_u32_e32 v13, 0x10a60, v142
	ds_read_b128 v[2:5], v197 offset:96
	ds_read_b128 v[6:9], v197 offset:112
	ds_read_b128 v[14:17], v13
	s_waitcnt lgkmcnt(0)
	v_pk_fma_f32 v[2:3], v[2:3], v[12:13], v[14:15] op_sel_hi:[1,0,1]
	s_nop 0
	v_mul_f32_e32 v13, 0xbfb8aa3b, v2
	v_exp_f32_e32 v14, v13
	v_mul_f32_e32 v13, 0xbfb8aa3b, v3
	v_exp_f32_e32 v15, v13
	s_nop 0
	v_pk_add_f32 v[14:15], v[14:15], 1.0 op_sel_hi:[1,0]
	s_nop 0
	v_rcp_f32_e32 v18, v15
	s_nop 0
	v_mul_f32_e32 v20, v3, v18
	v_fma_f32 v21, -v15, v20, v3
	v_fma_f32 v13, v21, v18, v20
	v_div_fixup_f32 v3, v13, v15, v3
	v_rcp_f32_e32 v15, v14
	s_nop 0
	v_mul_f32_e32 v19, v2, v15
	v_fma_f32 v20, -v14, v19, v2
	v_fma_f32 v13, v20, v15, v19
	v_div_fixup_f32 v2, v13, v14, v2
	v_pk_fma_f32 v[4:5], v[4:5], v[12:13], v[16:17] op_sel_hi:[1,0,1]
	v_cvt_pk_bf16_f32 v2, v2, v3
	v_mul_f32_e32 v3, 0xbfb8aa3b, v4
	v_exp_f32_e32 v14, v3
	v_mul_f32_e32 v3, 0xbfb8aa3b, v5
	v_exp_f32_e32 v15, v3
	s_nop 0
	v_pk_add_f32 v[14:15], v[14:15], 1.0 op_sel_hi:[1,0]
	s_nop 0
	v_rcp_f32_e32 v13, v15
	s_nop 0
	v_mul_f32_e32 v17, v5, v13
	v_fma_f32 v18, -v15, v17, v5
	v_fma_f32 v3, v18, v13, v17
	v_div_fixup_f32 v3, v3, v15, v5
	v_rcp_f32_e32 v13, v14
	s_nop 0
	v_mul_f32_e32 v16, v4, v13
	v_fma_f32 v17, -v14, v16, v4
	v_fma_f32 v5, v17, v13, v16
	v_div_fixup_f32 v4, v5, v14, v4
	v_cvt_pk_bf16_f32 v3, v4, v3
	v_add_u32_e32 v4, 0x10a70, v142
	ds_read_b128 v[14:17], v4
	s_waitcnt lgkmcnt(0)
	v_pk_fma_f32 v[4:5], v[6:7], v[12:13], v[14:15] op_sel_hi:[1,0,1]
	s_nop 0
	v_mul_f32_e32 v6, 0xbfb8aa3b, v4
	v_mul_f32_e32 v7, 0xbfb8aa3b, v5
	v_exp_f32_e32 v6, v6
	v_exp_f32_e32 v7, v7
	s_nop 0
	v_pk_add_f32 v[6:7], v[6:7], 1.0 op_sel_hi:[1,0]
	s_nop 0
	v_rcp_f32_e32 v14, v7
	s_nop 0
	v_mul_f32_e32 v18, v5, v14
	v_fma_f32 v19, -v7, v18, v5
	v_fma_f32 v13, v19, v14, v18
	v_div_fixup_f32 v5, v13, v7, v5
	v_rcp_f32_e32 v13, v6
	s_nop 0
	v_mul_f32_e32 v15, v4, v13
	v_fma_f32 v18, -v6, v15, v4
	v_fma_f32 v7, v18, v13, v15
	v_div_fixup_f32 v4, v7, v6, v4
	v_pk_fma_f32 v[6:7], v[8:9], v[12:13], v[16:17] op_sel_hi:[1,0,1]
	v_cvt_pk_bf16_f32 v4, v4, v5
	v_mul_f32_e32 v5, 0xbfb8aa3b, v6
	v_exp_f32_e32 v8, v5
	v_mul_f32_e32 v5, 0xbfb8aa3b, v7
	v_exp_f32_e32 v9, v5
	s_nop 0
	v_pk_add_f32 v[8:9], v[8:9], 1.0 op_sel_hi:[1,0]
	s_nop 0
	v_rcp_f32_e32 v13, v9
	s_nop 0
	v_mul_f32_e32 v15, v7, v13
	v_fma_f32 v16, -v9, v15, v7
	v_fma_f32 v5, v16, v13, v15
	v_div_fixup_f32 v5, v5, v9, v7
	v_rcp_f32_e32 v9, v8
	s_nop 0
	v_mul_f32_e32 v14, v6, v9
	v_fma_f32 v15, -v8, v14, v6
	v_fma_f32 v7, v15, v9, v14
	v_div_fixup_f32 v6, v7, v8, v6
	v_cvt_pk_bf16_f32 v5, v6, v5
	global_store_dwordx4 v[10:11], v[2:5], off offset:48
	v_add_u32_e32 v13, 0x10a80, v142
	ds_read_b128 v[2:5], v197 offset:128
	ds_read_b128 v[6:9], v197 offset:144
	ds_read_b128 v[14:17], v13
	s_waitcnt lgkmcnt(0)
	v_pk_fma_f32 v[2:3], v[2:3], v[12:13], v[14:15] op_sel_hi:[1,0,1]
	s_nop 0
	v_mul_f32_e32 v13, 0xbfb8aa3b, v2
	v_exp_f32_e32 v14, v13
	v_mul_f32_e32 v13, 0xbfb8aa3b, v3
	v_exp_f32_e32 v15, v13
	s_nop 0
	v_pk_add_f32 v[14:15], v[14:15], 1.0 op_sel_hi:[1,0]
	s_nop 0
	v_rcp_f32_e32 v18, v15
	s_nop 0
	v_mul_f32_e32 v20, v3, v18
	v_fma_f32 v21, -v15, v20, v3
	v_fma_f32 v13, v21, v18, v20
	v_div_fixup_f32 v3, v13, v15, v3
	v_rcp_f32_e32 v15, v14
	s_nop 0
	v_mul_f32_e32 v19, v2, v15
	v_fma_f32 v20, -v14, v19, v2
	v_fma_f32 v13, v20, v15, v19
	v_div_fixup_f32 v2, v13, v14, v2
	v_pk_fma_f32 v[4:5], v[4:5], v[12:13], v[16:17] op_sel_hi:[1,0,1]
	v_cvt_pk_bf16_f32 v2, v2, v3
	v_mul_f32_e32 v3, 0xbfb8aa3b, v4
	v_exp_f32_e32 v14, v3
	v_mul_f32_e32 v3, 0xbfb8aa3b, v5
	v_exp_f32_e32 v15, v3
	s_nop 0
	v_pk_add_f32 v[14:15], v[14:15], 1.0 op_sel_hi:[1,0]
	s_nop 0
	v_rcp_f32_e32 v13, v15
	s_nop 0
	v_mul_f32_e32 v17, v5, v13
	v_fma_f32 v18, -v15, v17, v5
	v_fma_f32 v3, v18, v13, v17
	v_div_fixup_f32 v3, v3, v15, v5
	v_rcp_f32_e32 v13, v14
	s_nop 0
	v_mul_f32_e32 v16, v4, v13
	v_fma_f32 v17, -v14, v16, v4
	v_fma_f32 v5, v17, v13, v16
	v_div_fixup_f32 v4, v5, v14, v4
	v_cvt_pk_bf16_f32 v3, v4, v3
	v_add_u32_e32 v4, 0x10a90, v142
	ds_read_b128 v[14:17], v4
	s_waitcnt lgkmcnt(0)
	v_pk_fma_f32 v[4:5], v[6:7], v[12:13], v[14:15] op_sel_hi:[1,0,1]
	s_nop 0
	v_mul_f32_e32 v6, 0xbfb8aa3b, v4
	v_mul_f32_e32 v7, 0xbfb8aa3b, v5
	v_exp_f32_e32 v6, v6
	v_exp_f32_e32 v7, v7
	s_nop 0
	v_pk_add_f32 v[6:7], v[6:7], 1.0 op_sel_hi:[1,0]
	s_nop 0
	v_rcp_f32_e32 v14, v7
	s_nop 0
	v_mul_f32_e32 v18, v5, v14
	v_fma_f32 v19, -v7, v18, v5
	v_fma_f32 v13, v19, v14, v18
	v_div_fixup_f32 v5, v13, v7, v5
	v_rcp_f32_e32 v13, v6
	s_nop 0
	v_mul_f32_e32 v15, v4, v13
	v_fma_f32 v18, -v6, v15, v4
	v_fma_f32 v7, v18, v13, v15
	v_div_fixup_f32 v4, v7, v6, v4
	v_pk_fma_f32 v[6:7], v[8:9], v[12:13], v[16:17] op_sel_hi:[1,0,1]
	v_cvt_pk_bf16_f32 v4, v4, v5
	v_mul_f32_e32 v5, 0xbfb8aa3b, v6
	v_exp_f32_e32 v8, v5
	v_mul_f32_e32 v5, 0xbfb8aa3b, v7
	v_exp_f32_e32 v9, v5
	s_nop 0
	v_pk_add_f32 v[8:9], v[8:9], 1.0 op_sel_hi:[1,0]
	s_nop 0
	v_rcp_f32_e32 v13, v9
	s_nop 0
	v_mul_f32_e32 v15, v7, v13
	v_fma_f32 v16, -v9, v15, v7
	v_fma_f32 v5, v16, v13, v15
	v_div_fixup_f32 v5, v5, v9, v7
	v_rcp_f32_e32 v9, v8
	s_nop 0
	v_mul_f32_e32 v14, v6, v9
	v_fma_f32 v15, -v8, v14, v6
	v_fma_f32 v7, v15, v9, v14
	v_div_fixup_f32 v6, v7, v8, v6
	v_cvt_pk_bf16_f32 v5, v6, v5
	global_store_dwordx4 v[10:11], v[2:5], off offset:64
	v_add_u32_e32 v13, 0x10aa0, v142
	ds_read_b128 v[2:5], v197 offset:160
	ds_read_b128 v[6:9], v197 offset:176
	ds_read_b128 v[14:17], v13
	s_waitcnt lgkmcnt(0)
	v_pk_fma_f32 v[2:3], v[2:3], v[12:13], v[14:15] op_sel_hi:[1,0,1]
	s_nop 0
	v_mul_f32_e32 v13, 0xbfb8aa3b, v2
	v_exp_f32_e32 v14, v13
	v_mul_f32_e32 v13, 0xbfb8aa3b, v3
	v_exp_f32_e32 v15, v13
	s_nop 0
	v_pk_add_f32 v[14:15], v[14:15], 1.0 op_sel_hi:[1,0]
	s_nop 0
	v_rcp_f32_e32 v18, v15
	s_nop 0
	v_mul_f32_e32 v20, v3, v18
	v_fma_f32 v21, -v15, v20, v3
	v_fma_f32 v13, v21, v18, v20
	v_div_fixup_f32 v3, v13, v15, v3
	v_rcp_f32_e32 v15, v14
	s_nop 0
	v_mul_f32_e32 v19, v2, v15
	v_fma_f32 v20, -v14, v19, v2
	v_fma_f32 v13, v20, v15, v19
	v_div_fixup_f32 v2, v13, v14, v2
	v_pk_fma_f32 v[4:5], v[4:5], v[12:13], v[16:17] op_sel_hi:[1,0,1]
	v_cvt_pk_bf16_f32 v2, v2, v3
	v_mul_f32_e32 v3, 0xbfb8aa3b, v4
	v_exp_f32_e32 v14, v3
	v_mul_f32_e32 v3, 0xbfb8aa3b, v5
	v_exp_f32_e32 v15, v3
	s_nop 0
	v_pk_add_f32 v[14:15], v[14:15], 1.0 op_sel_hi:[1,0]
	s_nop 0
	v_rcp_f32_e32 v13, v15
	s_nop 0
	v_mul_f32_e32 v17, v5, v13
	v_fma_f32 v18, -v15, v17, v5
	v_fma_f32 v3, v18, v13, v17
	v_div_fixup_f32 v3, v3, v15, v5
	v_rcp_f32_e32 v13, v14
	s_nop 0
	v_mul_f32_e32 v16, v4, v13
	v_fma_f32 v17, -v14, v16, v4
	v_fma_f32 v5, v17, v13, v16
	v_div_fixup_f32 v4, v5, v14, v4
	v_cvt_pk_bf16_f32 v3, v4, v3
	v_add_u32_e32 v4, 0x10ab0, v142
	ds_read_b128 v[14:17], v4
	s_waitcnt lgkmcnt(0)
	v_pk_fma_f32 v[4:5], v[6:7], v[12:13], v[14:15] op_sel_hi:[1,0,1]
	s_nop 0
	v_mul_f32_e32 v6, 0xbfb8aa3b, v4
	v_mul_f32_e32 v7, 0xbfb8aa3b, v5
	v_exp_f32_e32 v6, v6
	v_exp_f32_e32 v7, v7
	s_nop 0
	v_pk_add_f32 v[6:7], v[6:7], 1.0 op_sel_hi:[1,0]
	s_nop 0
	v_rcp_f32_e32 v14, v7
	s_nop 0
	v_mul_f32_e32 v18, v5, v14
	v_fma_f32 v19, -v7, v18, v5
	v_fma_f32 v13, v19, v14, v18
	v_div_fixup_f32 v5, v13, v7, v5
	v_rcp_f32_e32 v13, v6
	s_nop 0
	v_mul_f32_e32 v15, v4, v13
	v_fma_f32 v18, -v6, v15, v4
	v_fma_f32 v7, v18, v13, v15
	v_div_fixup_f32 v4, v7, v6, v4
	v_pk_fma_f32 v[6:7], v[8:9], v[12:13], v[16:17] op_sel_hi:[1,0,1]
	v_cvt_pk_bf16_f32 v4, v4, v5
	v_mul_f32_e32 v5, 0xbfb8aa3b, v6
	v_exp_f32_e32 v8, v5
	v_mul_f32_e32 v5, 0xbfb8aa3b, v7
	v_exp_f32_e32 v9, v5
	s_nop 0
	v_pk_add_f32 v[8:9], v[8:9], 1.0 op_sel_hi:[1,0]
	s_nop 0
	v_rcp_f32_e32 v13, v9
	s_nop 0
	v_mul_f32_e32 v15, v7, v13
	v_fma_f32 v16, -v9, v15, v7
	v_fma_f32 v5, v16, v13, v15
	v_div_fixup_f32 v5, v5, v9, v7
	v_rcp_f32_e32 v9, v8
	s_nop 0
	v_mul_f32_e32 v14, v6, v9
	v_fma_f32 v15, -v8, v14, v6
	v_fma_f32 v7, v15, v9, v14
	v_div_fixup_f32 v6, v7, v8, v6
	v_cvt_pk_bf16_f32 v5, v6, v5
	global_store_dwordx4 v[10:11], v[2:5], off offset:80
	v_add_u32_e32 v13, 0x10ac0, v142
	ds_read_b128 v[2:5], v197 offset:192
	ds_read_b128 v[6:9], v197 offset:208
	ds_read_b128 v[14:17], v13
	s_waitcnt lgkmcnt(0)
	v_pk_fma_f32 v[2:3], v[2:3], v[12:13], v[14:15] op_sel_hi:[1,0,1]
	s_nop 0
	v_mul_f32_e32 v13, 0xbfb8aa3b, v2
	v_exp_f32_e32 v14, v13
	v_mul_f32_e32 v13, 0xbfb8aa3b, v3
	v_exp_f32_e32 v15, v13
	s_nop 0
	v_pk_add_f32 v[14:15], v[14:15], 1.0 op_sel_hi:[1,0]
	s_nop 0
	v_rcp_f32_e32 v18, v15
	s_nop 0
	v_mul_f32_e32 v20, v3, v18
	v_fma_f32 v21, -v15, v20, v3
	v_fma_f32 v13, v21, v18, v20
	v_div_fixup_f32 v3, v13, v15, v3
	v_rcp_f32_e32 v15, v14
	s_nop 0
	v_mul_f32_e32 v19, v2, v15
	v_fma_f32 v20, -v14, v19, v2
	v_fma_f32 v13, v20, v15, v19
	v_div_fixup_f32 v2, v13, v14, v2
	v_pk_fma_f32 v[4:5], v[4:5], v[12:13], v[16:17] op_sel_hi:[1,0,1]
	v_cvt_pk_bf16_f32 v2, v2, v3
	v_mul_f32_e32 v3, 0xbfb8aa3b, v4
	v_exp_f32_e32 v14, v3
	v_mul_f32_e32 v3, 0xbfb8aa3b, v5
	v_exp_f32_e32 v15, v3
	s_nop 0
	v_pk_add_f32 v[14:15], v[14:15], 1.0 op_sel_hi:[1,0]
	s_nop 0
	v_rcp_f32_e32 v13, v15
	s_nop 0
	v_mul_f32_e32 v17, v5, v13
	v_fma_f32 v18, -v15, v17, v5
	v_fma_f32 v3, v18, v13, v17
	v_div_fixup_f32 v3, v3, v15, v5
	v_rcp_f32_e32 v13, v14
	s_nop 0
	v_mul_f32_e32 v16, v4, v13
	v_fma_f32 v17, -v14, v16, v4
	v_fma_f32 v5, v17, v13, v16
	v_div_fixup_f32 v4, v5, v14, v4
	v_cvt_pk_bf16_f32 v3, v4, v3
	v_add_u32_e32 v4, 0x10ad0, v142
	ds_read_b128 v[14:17], v4
	s_waitcnt lgkmcnt(0)
	v_pk_fma_f32 v[4:5], v[6:7], v[12:13], v[14:15] op_sel_hi:[1,0,1]
	s_nop 0
	v_mul_f32_e32 v6, 0xbfb8aa3b, v4
	v_mul_f32_e32 v7, 0xbfb8aa3b, v5
	v_exp_f32_e32 v6, v6
	v_exp_f32_e32 v7, v7
	s_nop 0
	v_pk_add_f32 v[6:7], v[6:7], 1.0 op_sel_hi:[1,0]
	s_nop 0
	v_rcp_f32_e32 v14, v7
	s_nop 0
	v_mul_f32_e32 v18, v5, v14
	v_fma_f32 v19, -v7, v18, v5
	v_fma_f32 v13, v19, v14, v18
	v_div_fixup_f32 v5, v13, v7, v5
	v_rcp_f32_e32 v13, v6
	s_nop 0
	v_mul_f32_e32 v15, v4, v13
	v_fma_f32 v18, -v6, v15, v4
	v_fma_f32 v7, v18, v13, v15
	v_div_fixup_f32 v4, v7, v6, v4
	v_pk_fma_f32 v[6:7], v[8:9], v[12:13], v[16:17] op_sel_hi:[1,0,1]
	v_cvt_pk_bf16_f32 v4, v4, v5
	v_mul_f32_e32 v5, 0xbfb8aa3b, v6
	v_exp_f32_e32 v8, v5
	v_mul_f32_e32 v5, 0xbfb8aa3b, v7
	v_exp_f32_e32 v9, v5
	s_nop 0
	v_pk_add_f32 v[8:9], v[8:9], 1.0 op_sel_hi:[1,0]
	s_nop 0
	v_rcp_f32_e32 v13, v9
	s_nop 0
	v_mul_f32_e32 v15, v7, v13
	v_fma_f32 v16, -v9, v15, v7
	v_fma_f32 v5, v16, v13, v15
	v_div_fixup_f32 v5, v5, v9, v7
	v_rcp_f32_e32 v9, v8
	s_nop 0
	v_mul_f32_e32 v14, v6, v9
	v_fma_f32 v15, -v8, v14, v6
	v_fma_f32 v7, v15, v9, v14
	v_div_fixup_f32 v6, v7, v8, v6
	v_cvt_pk_bf16_f32 v5, v6, v5
	global_store_dwordx4 v[10:11], v[2:5], off offset:96
	v_add_u32_e32 v13, 0x10ae0, v142
	ds_read_b128 v[2:5], v197 offset:224
	ds_read_b128 v[6:9], v197 offset:240
	ds_read_b128 v[14:17], v13
	s_waitcnt lgkmcnt(0)
	v_pk_fma_f32 v[2:3], v[2:3], v[12:13], v[14:15] op_sel_hi:[1,0,1]
	s_nop 0
	v_mul_f32_e32 v13, 0xbfb8aa3b, v2
	v_exp_f32_e32 v14, v13
	v_mul_f32_e32 v13, 0xbfb8aa3b, v3
	v_exp_f32_e32 v15, v13
	s_nop 0
	v_pk_add_f32 v[14:15], v[14:15], 1.0 op_sel_hi:[1,0]
	s_nop 0
	v_rcp_f32_e32 v18, v15
	s_nop 0
	v_mul_f32_e32 v20, v3, v18
	v_fma_f32 v21, -v15, v20, v3
	v_fma_f32 v13, v21, v18, v20
	v_div_fixup_f32 v3, v13, v15, v3
	v_rcp_f32_e32 v15, v14
	s_nop 0
	v_mul_f32_e32 v19, v2, v15
	v_fma_f32 v20, -v14, v19, v2
	v_fma_f32 v13, v20, v15, v19
	v_div_fixup_f32 v2, v13, v14, v2
	v_pk_fma_f32 v[4:5], v[4:5], v[12:13], v[16:17] op_sel_hi:[1,0,1]
	v_cvt_pk_bf16_f32 v2, v2, v3
	v_mul_f32_e32 v3, 0xbfb8aa3b, v4
	v_exp_f32_e32 v14, v3
	v_mul_f32_e32 v3, 0xbfb8aa3b, v5
	v_exp_f32_e32 v15, v3
	s_nop 0
	v_pk_add_f32 v[14:15], v[14:15], 1.0 op_sel_hi:[1,0]
	s_nop 0
	v_rcp_f32_e32 v13, v15
	s_nop 0
	v_mul_f32_e32 v17, v5, v13
	v_fma_f32 v18, -v15, v17, v5
	v_fma_f32 v3, v18, v13, v17
	v_div_fixup_f32 v3, v3, v15, v5
	v_rcp_f32_e32 v13, v14
	s_nop 0
	v_mul_f32_e32 v16, v4, v13
	v_fma_f32 v17, -v14, v16, v4
	v_fma_f32 v5, v17, v13, v16
	v_div_fixup_f32 v4, v5, v14, v4
	v_cvt_pk_bf16_f32 v3, v4, v3
	v_add_u32_e32 v4, 0x10af0, v142
	ds_read_b128 v[14:17], v4
	s_waitcnt lgkmcnt(0)
	v_pk_fma_f32 v[4:5], v[6:7], v[12:13], v[14:15] op_sel_hi:[1,0,1]
	s_nop 0
	v_mul_f32_e32 v6, 0xbfb8aa3b, v4
	v_mul_f32_e32 v7, 0xbfb8aa3b, v5
	v_exp_f32_e32 v6, v6
	v_exp_f32_e32 v7, v7
	s_nop 0
	v_pk_add_f32 v[6:7], v[6:7], 1.0 op_sel_hi:[1,0]
	s_nop 0
	v_rcp_f32_e32 v14, v7
	s_nop 0
	v_mul_f32_e32 v18, v5, v14
	v_fma_f32 v19, -v7, v18, v5
	v_fma_f32 v13, v19, v14, v18
	v_div_fixup_f32 v5, v13, v7, v5
	v_rcp_f32_e32 v13, v6
	s_nop 0
	v_mul_f32_e32 v15, v4, v13
	v_fma_f32 v18, -v6, v15, v4
	v_fma_f32 v7, v18, v13, v15
	v_div_fixup_f32 v4, v7, v6, v4
	v_pk_fma_f32 v[6:7], v[8:9], v[12:13], v[16:17] op_sel_hi:[1,0,1]
	v_cvt_pk_bf16_f32 v4, v4, v5
	v_mul_f32_e32 v5, 0xbfb8aa3b, v6
	v_exp_f32_e32 v8, v5
	v_mul_f32_e32 v5, 0xbfb8aa3b, v7
	v_exp_f32_e32 v9, v5
	s_nop 0
	v_pk_add_f32 v[8:9], v[8:9], 1.0 op_sel_hi:[1,0]
	s_nop 0
	v_rcp_f32_e32 v12, v9
	s_nop 0
	v_mul_f32_e32 v14, v7, v12
	v_fma_f32 v15, -v9, v14, v7
	v_fma_f32 v5, v15, v12, v14
	v_div_fixup_f32 v5, v5, v9, v7
	v_div_scale_f32 v7, s[0:1], v8, v8, v6
	v_rcp_f32_e32 v9, v7
	s_mov_b64 s[0:1], 0
	v_fma_f32 v12, -v7, v9, 1.0
	v_fmac_f32_e32 v9, v12, v9
	v_div_scale_f32 v12, vcc, v6, v8, v6
	v_mul_f32_e32 v13, v12, v9
	v_fma_f32 v14, -v7, v13, v12
	v_fmac_f32_e32 v13, v14, v9
	v_fma_f32 v7, -v7, v13, v12
	v_div_fmas_f32 v7, v7, v9, v13
	v_div_fixup_f32 v6, v7, v8, v6
	v_cvt_pk_bf16_f32 v5, v6, v5
	global_store_dwordx4 v[10:11], v[2:5], off offset:112

.Ltail_211:
	ds_read_b128 v[98:101], v138
	ds_read_b128 v[102:105], v139 offset:36864
	ds_read_b128 v[106:109], v138 offset:32
	ds_read_b128 v[110:113], v139 offset:36896
	ds_read_b128 v[114:117], v139 offset:41472
	ds_read_b128 v[118:121], v138 offset:4608
	ds_read_b128 v[122:125], v138 offset:4640
	s_waitcnt vmcnt(0)
	ds_read_b128 v[126:129], v139 offset:41504
	ds_write_b128 v209, v[94:97] offset:18432
	s_waitcnt lgkmcnt(7)
	v_mfma_f32_32x32x16_bf16 v[50:65], v[98:101], v[102:105], v[50:65]
	s_waitcnt lgkmcnt(4)
	v_mfma_f32_32x32x16_bf16 v[34:49], v[98:101], v[114:117], v[34:49]
	s_waitcnt lgkmcnt(3)
	v_mfma_f32_32x32x16_bf16 v[18:33], v[118:121], v[102:105], v[18:33]
	ds_write_b128 v209, v[90:93] offset:55296
	v_mfma_f32_32x32x16_bf16 v[2:17], v[118:121], v[114:117], v[2:17]
	ds_read_b128 v[90:93], v138 offset:64
	ds_read_b128 v[94:97], v138 offset:4672
	ds_read_b128 v[98:101], v139 offset:36928
	ds_read_b128 v[102:105], v139 offset:41536
	v_mfma_f32_32x32x16_bf16 v[50:65], v[106:109], v[110:113], v[50:65]
	ds_write_b128 v209, v[86:89] offset:23040
	s_waitcnt lgkmcnt(7)
	v_mfma_f32_32x32x16_bf16 v[34:49], v[106:109], v[126:129], v[34:49]
	v_mfma_f32_32x32x16_bf16 v[18:33], v[122:125], v[110:113], v[18:33]
	ds_write_b128 v209, v[82:85] offset:59904
	v_mfma_f32_32x32x16_bf16 v[2:17], v[122:125], v[126:129], v[2:17]
	ds_read_b128 v[82:85], v138 offset:96
	ds_read_b128 v[86:89], v138 offset:4704
	ds_read_b128 v[106:109], v139 offset:36960
	ds_read_b128 v[110:113], v139 offset:41568
	s_waitcnt lgkmcnt(7)
	v_mfma_f32_32x32x16_bf16 v[50:65], v[90:93], v[98:101], v[50:65]
	ds_write_b128 v209, v[78:81] offset:27648
	s_waitcnt lgkmcnt(7)
	v_mfma_f32_32x32x16_bf16 v[34:49], v[90:93], v[102:105], v[34:49]
	v_mfma_f32_32x32x16_bf16 v[18:33], v[94:97], v[98:101], v[18:33]
	ds_write_b128 v209, v[74:77] offset:64512
	v_mfma_f32_32x32x16_bf16 v[2:17], v[94:97], v[102:105], v[2:17]
	s_waitcnt lgkmcnt(3)
	v_mfma_f32_32x32x16_bf16 v[50:65], v[82:85], v[106:109], v[50:65]
	ds_write_b128 v209, v[70:73] offset:32256
	s_waitcnt lgkmcnt(3)
	v_mfma_f32_32x32x16_bf16 v[34:49], v[82:85], v[110:113], v[34:49]
	v_mfma_f32_32x32x16_bf16 v[18:33], v[86:89], v[106:109], v[18:33]
	ds_write_b128 v212, v[66:69] offset:13824
	v_mfma_f32_32x32x16_bf16 v[2:17], v[86:89], v[110:113], v[2:17]
	s_waitcnt lgkmcnt(0)
	s_barrier
	ds_read_b128 v[66:69], v138 offset:18432
	ds_read_b128 v[70:73], v139 offset:55296
	ds_read_b128 v[74:77], v138 offset:18464
	ds_read_b128 v[78:81], v139 offset:55328
	ds_read_b128 v[82:85], v139 offset:59904
	ds_read_b128 v[86:89], v138 offset:23040
	ds_read_b128 v[90:93], v138 offset:23072
	ds_read_b128 v[94:97], v139 offset:59936
	s_waitcnt lgkmcnt(6)
	v_mfma_f32_32x32x16_bf16 v[50:65], v[66:69], v[70:73], v[50:65]
	s_waitcnt lgkmcnt(3)
	v_mfma_f32_32x32x16_bf16 v[34:49], v[66:69], v[82:85], v[34:49]
	s_waitcnt lgkmcnt(2)
	v_mfma_f32_32x32x16_bf16 v[18:33], v[86:89], v[70:73], v[18:33]
	v_mfma_f32_32x32x16_bf16 v[2:17], v[86:89], v[82:85], v[2:17]
	ds_read_b128 v[66:69], v138 offset:18496
	ds_read_b128 v[70:73], v138 offset:23104
	ds_read_b128 v[82:85], v139 offset:55360
	ds_read_b128 v[86:89], v139 offset:59968
	v_mfma_f32_32x32x16_bf16 v[50:65], v[74:77], v[78:81], v[50:65]
	s_waitcnt lgkmcnt(4)
	v_mfma_f32_32x32x16_bf16 v[34:49], v[74:77], v[94:97], v[34:49]
	v_mfma_f32_32x32x16_bf16 v[18:33], v[90:93], v[78:81], v[18:33]
	v_mfma_f32_32x32x16_bf16 v[2:17], v[90:93], v[94:97], v[2:17]
	ds_read_b128 v[74:77], v138 offset:18528
	ds_read_b128 v[78:81], v138 offset:23136
	ds_read_b128 v[90:93], v139 offset:55392
	ds_read_b128 v[94:97], v139 offset:60000
	s_waitcnt lgkmcnt(5)
	v_mfma_f32_32x32x16_bf16 v[50:65], v[66:69], v[82:85], v[50:65]
	s_waitcnt lgkmcnt(4)
	v_mfma_f32_32x32x16_bf16 v[34:49], v[66:69], v[86:89], v[34:49]
	v_mfma_f32_32x32x16_bf16 v[18:33], v[70:73], v[82:85], v[18:33]
	v_mfma_f32_32x32x16_bf16 v[2:17], v[70:73], v[86:89], v[2:17]
	s_waitcnt lgkmcnt(1)
	v_mfma_f32_32x32x16_bf16 v[50:65], v[74:77], v[90:93], v[50:65]
	s_waitcnt lgkmcnt(0)
	v_mfma_f32_32x32x16_bf16 v[34:49], v[74:77], v[94:97], v[34:49]
	v_mfma_f32_32x32x16_bf16 v[18:33], v[78:81], v[90:93], v[18:33]
	v_mfma_f32_32x32x16_bf16 v[2:17], v[78:81], v[94:97], v[2:17]
	v_lshl_or_b32 v66, v208, 2, v211
	s_movk_i32 s0, 0x210
	v_and_or_b32 v67, v151, 64, v207
	v_mul_lo_u32 v66, v66, s0
	v_lshl_add_u32 v66, v67, 2, v66
	s_barrier
	s_nop 3
	ds_write2_b32 v66, v50, v34 offset1:32
	ds_write2_b32 v66, v51, v35 offset0:132 offset1:164
	v_add_u32_e32 v34, 0x400, v66
	ds_write2_b32 v34, v52, v36 offset0:8 offset1:40
	ds_write2_b32 v34, v53, v37 offset0:140 offset1:172
	v_add_u32_e32 v34, 0x1000, v66
	ds_write2_b32 v34, v54, v38 offset0:32 offset1:64
	ds_write2_b32 v34, v55, v39 offset0:164 offset1:196
	v_add_u32_e32 v34, 0x1400, v66
	ds_write2_b32 v34, v56, v40 offset0:40 offset1:72
	ds_write2_b32 v34, v57, v41 offset0:172 offset1:204
	v_add_u32_e32 v34, 0x2000, v66
	ds_write2_b32 v34, v58, v42 offset0:64 offset1:96
	ds_write2_b32 v34, v59, v43 offset0:196 offset1:228
	v_add_u32_e32 v34, 0x2400, v66
	ds_write2_b32 v34, v60, v44 offset0:72 offset1:104
	ds_write2_b32 v34, v61, v45 offset0:204 offset1:236
	v_add_u32_e32 v34, 0x3000, v66
	ds_write2_b32 v34, v62, v46 offset0:96 offset1:128
	v_add_u32_e32 v34, 0x3200, v66
	ds_write2_b32 v34, v63, v47 offset0:100 offset1:132
	v_add_u32_e32 v34, 0x3400, v66
	ds_write2_b32 v34, v64, v48 offset0:104 offset1:136
	v_add_u32_e32 v34, 0x3600, v66
	ds_write2_b32 v34, v65, v49 offset0:108 offset1:140
	v_add_u32_e32 v34, 0x4000, v66
	ds_write2_b32 v34, v18, v2 offset0:128 offset1:160
	v_add_u32_e32 v2, 0x4400, v66
	ds_write2_b32 v2, v19, v3 offset0:4 offset1:36
	ds_write2_b32 v2, v20, v4 offset0:136 offset1:168
	v_add_u32_e32 v2, 0x4800, v66
	ds_write2_b32 v2, v21, v5 offset0:12 offset1:44
	v_add_u32_e32 v2, 0x5000, v66
	ds_write2_b32 v2, v22, v6 offset0:160 offset1:192
	v_add_u32_e32 v2, 0x5400, v66
	ds_write2_b32 v2, v23, v7 offset0:36 offset1:68
	ds_write2_b32 v2, v24, v8 offset0:168 offset1:200
	v_add_u32_e32 v2, 0x5800, v66
	ds_write2_b32 v2, v25, v9 offset0:44 offset1:76
	v_add_u32_e32 v2, 0x6000, v66
	ds_write2_b32 v2, v26, v10 offset0:192 offset1:224
	v_add_u32_e32 v2, 0x6400, v66
	ds_write2_b32 v2, v27, v11 offset0:68 offset1:100
	ds_write2_b32 v2, v28, v12 offset0:200 offset1:232
	v_add_u32_e32 v2, 0x6800, v66
	ds_write2_b32 v2, v29, v13 offset0:76 offset1:108
	v_add_u32_e32 v2, 0x7200, v66
	ds_write2_b32 v2, v30, v14 offset0:96 offset1:128
	v_add_u32_e32 v2, 0x7400, v66
	ds_write2_b32 v2, v31, v15 offset0:100 offset1:132
	v_add_u32_e32 v2, 0x7600, v66
	ds_write2_b32 v2, v32, v16 offset0:104 offset1:136
	v_add_u32_e32 v2, 0x7800, v66
	s_and_b64 vcc, exec, s[40:41]
	ds_write2_b32 v2, v33, v17 offset0:108 offset1:140
	s_waitcnt lgkmcnt(0)
	s_barrier
	s_cbranch_vccnz .LBB0_215
	s_mov_b32 s54, 0x10800
	ds_write_b32 v133, v146
	s_waitcnt lgkmcnt(0)
	s_barrier
	s_branch .LBB0_216
